# FFN-F2 epilogue: one-dword cache-warming loads for the second column half's gate rows issued with the first half's loads (placement-neutral padding)
# baseline (speedup 1.0000x reference)
.LBB0_1060:
	s_lshl_b32 s0, s3, 8
	s_add_i32 s0, s0, s60
	s_cmpk_lt_i32 s0, 0x2000
	s_movk_i32 s20, 0xfff
	v_lshl_or_b32 v192, s2, 8, v223
	s_cselect_b32 s14, s20, 0x7ff
	s_or_b32 s2, s0, 63
	s_and_b32 s1, s14, s0
	s_and_b32 s15, s14, s2
	v_or_b32_e32 v226, s0, v221
	v_mov_b64_e32 v[208:209], s[10:11]
	s_movk_i32 s26, 0x2c00
	v_ashrrev_i32_e32 v193, 31, v192
	v_mad_i64_i32 v[152:153], s[2:3], v226, s26, v[208:209]
	s_cmp_eq_u32 s1, 0
	s_mul_i32 s1, s0, 0x2c00
	v_lshlrev_b64 v[204:205], 1, v[192:193]
	s_cselect_b64 s[62:63], -1, 0
	s_mul_hi_i32 s3, s0, 0x2c00
	s_add_u32 s2, s10, s1
	v_lshl_add_u64 v[194:195], v[152:153], 0, v[204:205]
	s_mov_b32 s21, 0x2c000
	s_addc_u32 s3, s11, s3
	v_add_co_u32_e32 v198, vcc, s21, v194
	s_and_b64 s[12:13], s[62:63], exec
	s_nop 0
	v_addc_co_u32_e32 v199, vcc, 0, v195, vcc
	s_mov_b32 s22, 0x58000
	s_cselect_b32 s12, 0, 0xffffd400
	s_cselect_b32 s13, 0, -1
	s_cmp_eq_u32 s15, s14
	v_add_co_u32_e32 v200, vcc, s22, v194
	s_cselect_b64 s[50:51], -1, 0
	v_lshlrev_b64 v[88:89], 2, v[192:193]
	v_addc_co_u32_e32 v201, vcc, 0, v195, vcc
	s_mov_b32 s23, 0x84000
	v_lshl_add_u64 v[202:203], s[2:3], 0, v[204:205]
	s_and_b64 s[2:3], s[50:51], exec
	v_lshl_add_u64 v[190:191], s[18:19], 0, v[88:89]
	v_lshl_add_u64 v[90:91], s[46:47], 0, v[88:89]
	v_lshl_add_u64 v[96:97], s[48:49], 0, v[88:89]
	v_add_co_u32_e32 v206, vcc, s23, v194
	s_cselect_b32 s72, 0, 0xb0000
	v_lshl_add_u64 v[188:189], s[30:31], 0, v[88:89]
	global_load_dwordx4 v[100:103], v[190:191], off offset:16
	global_load_dwordx4 v[120:123], v[190:191], off
	global_load_dwordx4 v[92:95], v[90:91], off offset:16
	global_load_dwordx4 v[112:115], v[90:91], off
	s_nop 0
	global_load_dwordx4 v[88:91], v[96:97], off offset:16
	global_load_dwordx4 v[108:111], v[96:97], off
	s_nop 0
	global_load_dwordx4 v[96:99], v[188:189], off offset:16
	global_load_dwordx4 v[116:119], v[188:189], off
	global_load_dwordx4 v[172:175], v[194:195], off
	v_addc_co_u32_e32 v207, vcc, 0, v195, vcc
	v_lshl_add_u64 v[196:197], v[202:203], 0, s[12:13]
	v_lshl_add_u64 v[202:203], v[202:203], 0, s[72:73]
	global_load_dwordx4 v[168:171], v[198:199], off
	global_load_dwordx4 v[164:167], v[200:201], off
	global_load_dwordx4 v[152:155], v[206:207], off
	global_load_dwordx4 v[232:235], v[202:203], off
	global_load_dwordx4 v[228:231], v[196:197], off
	global_load_dword v253, v[194:195], off offset:256
	global_load_dword v253, v[198:199], off offset:256
	global_load_dword v253, v[200:201], off offset:256
	global_load_dword v253, v[206:207], off offset:256
	global_load_dword v253, v[202:203], off offset:256
	global_load_dword v253, v[196:197], off offset:256
	s_nop 0
	s_nop 0
	s_nop 0
	s_nop 0
	v_or_b32_e32 v193, v211, v219
	v_lshlrev_b32_e32 v193, 2, v193
	v_or_b32_e32 v225, v219, v212
	v_lshlrev_b32_e32 v225, 2, v225
	s_add_i32 s12, s0, 0x80
	s_cmpk_lt_i32 s12, 0x2000
	s_cselect_b32 s13, s20, 0x7ff
	s_addk_i32 s0, 0xbf
	s_and_b32 s14, s13, s12
	s_and_b32 s15, s13, s0
	s_cmp_eq_u32 s14, 0
	s_waitcnt vmcnt(0)
	ds_bpermute_b32 v239, v193, v172
	ds_bpermute_b32 v240, v193, v173
	ds_bpermute_b32 v241, v193, v174
	ds_bpermute_b32 v242, v193, v175
	ds_bpermute_b32 v243, v225, v168
	ds_bpermute_b32 v244, v225, v169
	ds_bpermute_b32 v245, v225, v170
	v_cndmask_b32_e64 v227, v235, 0, s[50:51]
	v_cndmask_b32_e64 v236, v230, 0, s[62:63]
	v_cndmask_b32_e64 v237, v229, 0, s[62:63]
	v_cndmask_b32_e64 v229, v233, 0, s[50:51]
	v_cndmask_b32_e64 v230, v232, 0, s[50:51]
	ds_bpermute_b32 v232, v225, v172
	ds_bpermute_b32 v233, v225, v173
	v_cndmask_b32_e64 v238, v228, 0, s[62:63]
	v_cndmask_b32_e64 v228, v234, 0, s[50:51]
	ds_bpermute_b32 v234, v225, v174
	ds_bpermute_b32 v235, v225, v175
	ds_bpermute_b32 v246, v225, v171
	s_waitcnt lgkmcnt(11)
	v_cndmask_b32_e64 v238, v239, v238, s[4:5]
	s_waitcnt lgkmcnt(4)
	v_cndmask_b32_e64 v247, v232, v243, s[6:7]
	s_waitcnt lgkmcnt(3)
	v_cndmask_b32_e64 v249, v233, v244, s[6:7]
	v_lshlrev_b32_e32 v232, 16, v238
	v_and_b32_e32 v233, 0xffff0000, v238
	v_cndmask_b32_e64 v248, v240, v237, s[4:5]
	v_cndmask_b32_e64 v250, v241, v236, s[4:5]
	v_pk_mul_f32 v[232:233], v[120:121], v[232:233]
	v_lshlrev_b32_e32 v236, 16, v172
	v_and_b32_e32 v237, 0xffff0000, v172
	s_waitcnt lgkmcnt(2)
	v_cndmask_b32_e64 v251, v234, v245, s[6:7]
	s_waitcnt lgkmcnt(0)
	v_cndmask_b32_e64 v252, v235, v246, s[6:7]
	v_lshlrev_b32_e32 v234, 16, v247
	v_and_b32_e32 v235, 0xffff0000, v247
	v_pk_fma_f32 v[232:233], v[112:113], v[236:237], v[232:233]
	v_cndmask_b32_e64 v231, v231, 0, s[62:63]
	v_pk_fma_f32 v[232:233], v[108:109], v[234:235], v[232:233]
	v_cndmask_b32_e64 v231, v242, v231, s[4:5]
	v_pk_add_f32 v[232:233], v[116:117], v[232:233]
	ds_bpermute_b32 v236, v225, v166
	v_mul_f32_e32 v172, 0xbfb8aa3b, v232
	v_exp_f32_e32 v172, v172
	ds_bpermute_b32 v237, v225, v167
	v_add_f32_e32 v172, 1.0, v172
	v_rcp_f32_e32 v234, v172
	v_mul_f32_e32 v172, 0xbfb8aa3b, v233
	v_exp_f32_e32 v172, v172
	s_nop 0
	v_add_f32_e32 v172, 1.0, v172
	v_rcp_f32_e32 v235, v172
	v_lshlrev_b32_e32 v172, 16, v173
	v_and_b32_e32 v173, 0xffff0000, v173
	v_pk_mul_f32 v[232:233], v[232:233], v[234:235]
	s_nop 0
	v_pk_mul_f32 v[160:161], v[160:161], v[232:233]
	v_lshlrev_b32_e32 v232, 16, v248
	v_and_b32_e32 v233, 0xffff0000, v248
	v_pk_mul_f32 v[232:233], v[122:123], v[232:233]
	v_lshlrev_b32_e32 v234, 16, v249
	v_and_b32_e32 v235, 0xffff0000, v249
	v_pk_fma_f32 v[172:173], v[114:115], v[172:173], v[232:233]
	s_nop 0
	v_pk_fma_f32 v[172:173], v[110:111], v[234:235], v[172:173]
	v_lshlrev_b32_e32 v234, 16, v174
	v_pk_add_f32 v[172:173], v[118:119], v[172:173]
	v_and_b32_e32 v235, 0xffff0000, v174
	v_mul_f32_e32 v232, 0xbfb8aa3b, v172
	v_mul_f32_e32 v233, 0xbfb8aa3b, v173
	v_exp_f32_e32 v232, v232
	v_exp_f32_e32 v233, v233
	v_add_f32_e32 v232, 1.0, v232
	v_add_f32_e32 v233, 1.0, v233
	v_rcp_f32_e32 v232, v232
	v_rcp_f32_e32 v233, v233
	s_nop 0
	v_pk_mul_f32 v[172:173], v[172:173], v[232:233]
	s_nop 0
	v_pk_mul_f32 v[162:163], v[162:163], v[172:173]
	v_lshlrev_b32_e32 v172, 16, v250
	v_and_b32_e32 v173, 0xffff0000, v250
	v_pk_mul_f32 v[172:173], v[100:101], v[172:173]
	v_lshlrev_b32_e32 v232, 16, v251
	v_and_b32_e32 v233, 0xffff0000, v251
	v_pk_fma_f32 v[172:173], v[92:93], v[234:235], v[172:173]
	ds_bpermute_b32 v234, v225, v164
	v_pk_fma_f32 v[172:173], v[88:89], v[232:233], v[172:173]
	ds_bpermute_b32 v235, v225, v165
	v_pk_add_f32 v[172:173], v[96:97], v[172:173]
	s_nop 0
	v_mul_f32_e32 v174, 0xbfb8aa3b, v172
	v_exp_f32_e32 v174, v174
	s_nop 0
	v_add_f32_e32 v174, 1.0, v174
	v_rcp_f32_e32 v232, v174
	v_mul_f32_e32 v174, 0xbfb8aa3b, v173
	v_exp_f32_e32 v174, v174
	s_nop 0
	v_add_f32_e32 v174, 1.0, v174
	v_rcp_f32_e32 v233, v174
	v_lshlrev_b32_e32 v174, 16, v175
	v_and_b32_e32 v175, 0xffff0000, v175
	v_pk_mul_f32 v[172:173], v[172:173], v[232:233]
	s_nop 0
	v_pk_mul_f32 v[156:157], v[156:157], v[172:173]
	v_lshlrev_b32_e32 v172, 16, v231
	v_and_b32_e32 v173, 0xffff0000, v231
	v_pk_mul_f32 v[172:173], v[102:103], v[172:173]
	v_lshlrev_b32_e32 v232, 16, v252
	v_and_b32_e32 v233, 0xffff0000, v252
	v_pk_fma_f32 v[172:173], v[94:95], v[174:175], v[172:173]
	ds_bpermute_b32 v231, v193, v170
	v_pk_fma_f32 v[172:173], v[90:91], v[232:233], v[172:173]
	ds_bpermute_b32 v232, v193, v171
	v_pk_add_f32 v[172:173], v[98:99], v[172:173]
	v_or_b32_e32 v233, 16, v226
	v_mul_f32_e32 v174, 0xbfb8aa3b, v172
	v_mul_f32_e32 v175, 0xbfb8aa3b, v173
	v_exp_f32_e32 v174, v174
	v_exp_f32_e32 v175, v175
	s_waitcnt lgkmcnt(0)
	v_cndmask_b32_e64 v242, v232, v242, s[4:5]
	v_add_f32_e32 v174, 1.0, v174
	v_add_f32_e32 v175, 1.0, v175
	v_rcp_f32_e32 v174, v174
	v_rcp_f32_e32 v175, v175
	s_nop 0
	v_pk_mul_f32 v[172:173], v[172:173], v[174:175]
	ds_bpermute_b32 v174, v193, v168
	v_pk_mul_f32 v[172:173], v[158:159], v[172:173]
	v_cvt_pk_bf16_f32 v158, v160, v161
	v_cvt_pk_bf16_f32 v161, v172, v173
	v_mov_b64_e32 v[172:173], s[16:17]
	v_cvt_pk_bf16_f32 v160, v156, v157
	v_mad_i64_i32 v[156:157], s[2:3], v226, s26, v[172:173]
	v_cvt_pk_bf16_f32 v159, v162, v163
	v_lshl_add_u64 v[156:157], v[156:157], 0, v[204:205]
	global_store_dwordx4 v[156:157], v[158:161], off
	v_lshlrev_b32_e32 v162, 16, v168
	v_and_b32_e32 v163, 0xffff0000, v168
	s_waitcnt lgkmcnt(0)
	v_cndmask_b32_e64 v159, v174, v239, s[4:5]
	v_lshlrev_b32_e32 v158, 16, v159
	v_and_b32_e32 v159, 0xffff0000, v159
	v_cndmask_b32_e64 v161, v243, v234, s[6:7]
	v_pk_mul_f32 v[158:159], v[120:121], v[158:159]
	v_lshlrev_b32_e32 v160, 16, v161
	v_and_b32_e32 v161, 0xffff0000, v161
	v_pk_fma_f32 v[158:159], v[112:113], v[162:163], v[158:159]
	ds_bpermute_b32 v175, v193, v169
	v_pk_fma_f32 v[158:159], v[108:109], v[160:161], v[158:159]
	v_cndmask_b32_e64 v239, v244, v235, s[6:7]
	v_pk_add_f32 v[158:159], v[116:117], v[158:159]
	v_lshlrev_b32_e32 v162, 16, v169
	v_mul_f32_e32 v160, 0xbfb8aa3b, v158
	v_mul_f32_e32 v161, 0xbfb8aa3b, v159
	v_exp_f32_e32 v160, v160
	v_exp_f32_e32 v161, v161
	s_waitcnt lgkmcnt(0)
	v_cndmask_b32_e64 v238, v175, v240, s[4:5]
	v_and_b32_e32 v163, 0xffff0000, v169
	v_add_f32_e32 v160, 1.0, v160
	v_add_f32_e32 v161, 1.0, v161
	v_rcp_f32_e32 v160, v160
	v_rcp_f32_e32 v161, v161
	v_cndmask_b32_e64 v240, v231, v241, s[4:5]
	v_cndmask_b32_e64 v241, v245, v236, s[6:7]
	v_cndmask_b32_e64 v243, v246, v237, s[6:7]
	v_pk_mul_f32 v[158:159], v[158:159], v[160:161]
	v_lshlrev_b32_e32 v160, 16, v239
	v_pk_mul_f32 v[148:149], v[148:149], v[158:159]
	v_lshlrev_b32_e32 v158, 16, v238
	v_and_b32_e32 v159, 0xffff0000, v238
	v_pk_mul_f32 v[158:159], v[122:123], v[158:159]
	v_and_b32_e32 v161, 0xffff0000, v239
	v_pk_fma_f32 v[158:159], v[114:115], v[162:163], v[158:159]
	v_lshlrev_b32_e32 v162, 16, v170
	v_pk_fma_f32 v[158:159], v[110:111], v[160:161], v[158:159]
	v_and_b32_e32 v163, 0xffff0000, v170
	v_pk_add_f32 v[158:159], v[118:119], v[158:159]
	v_cvt_pk_bf16_f32 v148, v148, v149
	v_mul_f32_e32 v160, 0xbfb8aa3b, v158
	v_mul_f32_e32 v161, 0xbfb8aa3b, v159
	v_exp_f32_e32 v160, v160
	v_exp_f32_e32 v161, v161
	ds_bpermute_b32 v168, v225, v153
	ds_bpermute_b32 v169, v225, v154
	v_add_f32_e32 v160, 1.0, v160
	v_add_f32_e32 v161, 1.0, v161
	v_rcp_f32_e32 v160, v160
	v_rcp_f32_e32 v161, v161
	ds_bpermute_b32 v170, v225, v155
	v_pk_mul_f32 v[158:159], v[158:159], v[160:161]
	s_nop 0
	v_pk_mul_f32 v[150:151], v[150:151], v[158:159]
	v_lshlrev_b32_e32 v158, 16, v240
	v_and_b32_e32 v159, 0xffff0000, v240
	v_pk_mul_f32 v[158:159], v[100:101], v[158:159]
	v_lshlrev_b32_e32 v160, 16, v241
	v_and_b32_e32 v161, 0xffff0000, v241
	v_pk_fma_f32 v[158:159], v[92:93], v[162:163], v[158:159]
	v_lshlrev_b32_e32 v162, 16, v171
	v_pk_fma_f32 v[158:159], v[88:89], v[160:161], v[158:159]
	v_and_b32_e32 v163, 0xffff0000, v171
	v_pk_add_f32 v[158:159], v[96:97], v[158:159]
	v_cvt_pk_bf16_f32 v149, v150, v151
	v_mul_f32_e32 v160, 0xbfb8aa3b, v158
	v_mul_f32_e32 v161, 0xbfb8aa3b, v159
	v_exp_f32_e32 v160, v160
	v_exp_f32_e32 v161, v161
	v_add_f32_e32 v160, 1.0, v160
	v_add_f32_e32 v161, 1.0, v161
	v_rcp_f32_e32 v160, v160
	v_rcp_f32_e32 v161, v161
	s_nop 0
	v_pk_mul_f32 v[158:159], v[158:159], v[160:161]
	s_nop 0
	v_pk_mul_f32 v[144:145], v[144:145], v[158:159]
	v_lshlrev_b32_e32 v158, 16, v242
	v_and_b32_e32 v159, 0xffff0000, v242
	v_pk_mul_f32 v[158:159], v[102:103], v[158:159]
	v_lshlrev_b32_e32 v160, 16, v243
	v_and_b32_e32 v161, 0xffff0000, v243
	v_pk_fma_f32 v[158:159], v[94:95], v[162:163], v[158:159]
	ds_bpermute_b32 v163, v225, v152
	v_pk_fma_f32 v[158:159], v[90:91], v[160:161], v[158:159]
	v_cvt_pk_bf16_f32 v150, v144, v145
	v_pk_add_f32 v[158:159], v[98:99], v[158:159]
	v_mad_i64_i32 v[144:145], s[2:3], v233, s26, v[172:173]
	v_mul_f32_e32 v160, 0xbfb8aa3b, v158
	v_mul_f32_e32 v161, 0xbfb8aa3b, v159
	v_exp_f32_e32 v160, v160
	v_exp_f32_e32 v161, v161
	s_waitcnt lgkmcnt(1)
	v_cndmask_b32_e64 v233, v237, v170, s[6:7]
	v_or_b32_e32 v162, 32, v226
	v_add_f32_e32 v160, 1.0, v160
	v_add_f32_e32 v161, 1.0, v161
	v_rcp_f32_e32 v160, v160
	v_rcp_f32_e32 v161, v161
	s_nop 0
	v_pk_mul_f32 v[158:159], v[158:159], v[160:161]
	s_nop 0
	v_pk_mul_f32 v[146:147], v[146:147], v[158:159]
	ds_bpermute_b32 v158, v193, v164
	v_cvt_pk_bf16_f32 v151, v146, v147
	v_lshl_add_u64 v[146:147], v[144:145], 0, v[204:205]
	global_store_dwordx4 v[146:147], v[148:151], off
	ds_bpermute_b32 v159, v193, v165
	s_waitcnt lgkmcnt(1)
	v_cndmask_b32_e64 v145, v158, v174, s[4:5]
	v_lshlrev_b32_e32 v144, 16, v145
	v_and_b32_e32 v145, 0xffff0000, v145
	v_cndmask_b32_e64 v149, v234, v163, s[6:7]
	v_pk_mul_f32 v[144:145], v[120:121], v[144:145]
	v_lshlrev_b32_e32 v150, 16, v164
	v_and_b32_e32 v151, 0xffff0000, v164
	v_lshlrev_b32_e32 v148, 16, v149
	v_and_b32_e32 v149, 0xffff0000, v149
	v_pk_fma_f32 v[144:145], v[112:113], v[150:151], v[144:145]
	s_waitcnt lgkmcnt(0)
	v_cndmask_b32_e64 v171, v159, v175, s[4:5]
	v_pk_fma_f32 v[144:145], v[108:109], v[148:149], v[144:145]
	v_cndmask_b32_e64 v174, v235, v168, s[6:7]
	v_pk_add_f32 v[144:145], v[116:117], v[144:145]
	v_lshlrev_b32_e32 v150, 16, v165
	v_mul_f32_e32 v148, 0xbfb8aa3b, v144
	v_mul_f32_e32 v149, 0xbfb8aa3b, v145
	v_exp_f32_e32 v148, v148
	v_exp_f32_e32 v149, v149
	v_and_b32_e32 v151, 0xffff0000, v165
	ds_bpermute_b32 v160, v193, v166
	v_add_f32_e32 v148, 1.0, v148
	v_add_f32_e32 v149, 1.0, v149
	v_rcp_f32_e32 v148, v148
	v_rcp_f32_e32 v149, v149
	s_waitcnt lgkmcnt(0)
	v_cndmask_b32_e64 v175, v160, v231, s[4:5]
	v_cndmask_b32_e64 v231, v236, v169, s[6:7]
	ds_bpermute_b32 v161, v193, v167
	v_pk_mul_f32 v[144:145], v[144:145], v[148:149]
	v_lshlrev_b32_e32 v148, 16, v174
	v_pk_mul_f32 v[140:141], v[140:141], v[144:145]
	v_lshlrev_b32_e32 v144, 16, v171
	v_and_b32_e32 v145, 0xffff0000, v171
	v_pk_mul_f32 v[144:145], v[122:123], v[144:145]
	v_and_b32_e32 v149, 0xffff0000, v174
	v_pk_fma_f32 v[144:145], v[114:115], v[150:151], v[144:145]
	v_lshlrev_b32_e32 v150, 16, v166
	v_pk_fma_f32 v[144:145], v[110:111], v[148:149], v[144:145]
	v_and_b32_e32 v151, 0xffff0000, v166
	v_pk_add_f32 v[144:145], v[118:119], v[144:145]
	s_waitcnt lgkmcnt(0)
	v_cndmask_b32_e64 v232, v161, v232, s[4:5]
	v_mul_f32_e32 v148, 0xbfb8aa3b, v144
	v_mul_f32_e32 v149, 0xbfb8aa3b, v145
	v_exp_f32_e32 v148, v148
	v_exp_f32_e32 v149, v149
	v_or_b32_e32 v164, s12, v221
	v_add_f32_e32 v148, 1.0, v148
	v_add_f32_e32 v149, 1.0, v149
	v_rcp_f32_e32 v148, v148
	v_rcp_f32_e32 v149, v149
	s_nop 0
	v_pk_mul_f32 v[144:145], v[144:145], v[148:149]
	s_nop 0
	v_pk_mul_f32 v[142:143], v[142:143], v[144:145]
	v_lshlrev_b32_e32 v144, 16, v175
	v_and_b32_e32 v145, 0xffff0000, v175
	v_pk_mul_f32 v[144:145], v[100:101], v[144:145]
	v_lshlrev_b32_e32 v148, 16, v231
	v_and_b32_e32 v149, 0xffff0000, v231
	v_pk_fma_f32 v[144:145], v[92:93], v[150:151], v[144:145]
	v_lshlrev_b32_e32 v150, 16, v167
	v_pk_fma_f32 v[144:145], v[88:89], v[148:149], v[144:145]
	v_and_b32_e32 v151, 0xffff0000, v167
	v_pk_add_f32 v[144:145], v[96:97], v[144:145]
	s_nop 0
	v_mul_f32_e32 v148, 0xbfb8aa3b, v144
	v_mul_f32_e32 v149, 0xbfb8aa3b, v145
	v_exp_f32_e32 v148, v148
	v_exp_f32_e32 v149, v149
	v_add_f32_e32 v148, 1.0, v148
	v_add_f32_e32 v149, 1.0, v149
	v_rcp_f32_e32 v148, v148
	v_rcp_f32_e32 v149, v149
	s_nop 0
	v_pk_mul_f32 v[144:145], v[144:145], v[148:149]
	s_nop 0
	v_pk_mul_f32 v[144:145], v[136:137], v[144:145]
	v_lshlrev_b32_e32 v136, 16, v232
	v_and_b32_e32 v137, 0xffff0000, v232
	v_pk_mul_f32 v[136:137], v[102:103], v[136:137]
	v_lshlrev_b32_e32 v148, 16, v233
	v_and_b32_e32 v149, 0xffff0000, v233
	v_pk_fma_f32 v[136:137], v[94:95], v[150:151], v[136:137]
	v_cndmask_b32_e64 v150, v169, v228, s[6:7]
	v_pk_fma_f32 v[136:137], v[90:91], v[148:149], v[136:137]
	s_nop 0
	v_pk_add_f32 v[136:137], v[98:99], v[136:137]
	s_nop 0
	v_mul_f32_e32 v148, 0xbfb8aa3b, v136
	v_mul_f32_e32 v149, 0xbfb8aa3b, v137
	v_exp_f32_e32 v148, v148
	v_exp_f32_e32 v149, v149
	v_add_f32_e32 v148, 1.0, v148
	v_add_f32_e32 v149, 1.0, v149
	v_rcp_f32_e32 v148, v148
	v_rcp_f32_e32 v149, v149
	s_nop 0
	v_pk_mul_f32 v[136:137], v[136:137], v[148:149]
	s_nop 0
	v_pk_mul_f32 v[148:149], v[138:139], v[136:137]
	v_cvt_pk_bf16_f32 v136, v140, v141
	v_mad_i64_i32 v[140:141], s[2:3], v162, s26, v[172:173]
	v_cvt_pk_bf16_f32 v137, v142, v143
	v_cvt_pk_bf16_f32 v138, v144, v145
	v_cvt_pk_bf16_f32 v139, v148, v149
	v_lshl_add_u64 v[148:149], v[140:141], 0, v[204:205]
	global_store_dwordx4 v[148:149], v[136:139], off
	ds_bpermute_b32 v136, v193, v152
	ds_bpermute_b32 v137, v193, v153
	ds_bpermute_b32 v138, v193, v154
	ds_bpermute_b32 v139, v193, v155
	v_cndmask_b32_e64 v141, v163, v230, s[6:7]
	s_waitcnt lgkmcnt(3)
	v_cndmask_b32_e64 v140, v136, v158, s[4:5]
	s_waitcnt lgkmcnt(2)
	v_cndmask_b32_e64 v143, v137, v159, s[4:5]
	v_lshlrev_b32_e32 v136, 16, v140
	v_and_b32_e32 v137, 0xffff0000, v140
	s_waitcnt lgkmcnt(1)
	v_cndmask_b32_e64 v145, v138, v160, s[4:5]
	s_waitcnt lgkmcnt(0)
	v_cndmask_b32_e64 v151, v139, v161, s[4:5]
	v_lshlrev_b32_e32 v138, 16, v141
	v_and_b32_e32 v139, 0xffff0000, v141
	v_pk_mul_f32 v[136:137], v[120:121], v[136:137]
	v_lshlrev_b32_e32 v140, 16, v152
	v_and_b32_e32 v141, 0xffff0000, v152
	v_pk_fma_f32 v[136:137], v[112:113], v[140:141], v[136:137]
	v_cndmask_b32_e64 v144, v168, v229, s[6:7]
	v_pk_fma_f32 v[136:137], v[108:109], v[138:139], v[136:137]
	v_lshlrev_b32_e32 v140, 16, v153
	v_pk_add_f32 v[136:137], v[116:117], v[136:137]
	v_and_b32_e32 v141, 0xffff0000, v153
	v_mul_f32_e32 v138, 0xbfb8aa3b, v136
	v_mul_f32_e32 v139, 0xbfb8aa3b, v137
	v_exp_f32_e32 v138, v138
	v_exp_f32_e32 v139, v139
	v_cndmask_b32_e64 v158, v170, v227, s[6:7]
	v_or_b32_e32 v142, 48, v226
	v_add_f32_e32 v138, 1.0, v138
	v_add_f32_e32 v139, 1.0, v139
	v_rcp_f32_e32 v138, v138
	v_rcp_f32_e32 v139, v139
	s_nop 0
	v_pk_mul_f32 v[136:137], v[136:137], v[138:139]
	s_nop 0
	v_pk_mul_f32 v[132:133], v[132:133], v[136:137]
	v_lshlrev_b32_e32 v136, 16, v143
	v_and_b32_e32 v137, 0xffff0000, v143
	v_pk_mul_f32 v[136:137], v[122:123], v[136:137]
	v_lshlrev_b32_e32 v138, 16, v144
	v_and_b32_e32 v139, 0xffff0000, v144
	v_pk_fma_f32 v[136:137], v[114:115], v[140:141], v[136:137]
	v_lshlrev_b32_e32 v140, 16, v154
	v_pk_fma_f32 v[136:137], v[110:111], v[138:139], v[136:137]
	v_and_b32_e32 v141, 0xffff0000, v154
	v_pk_add_f32 v[136:137], v[118:119], v[136:137]
	s_nop 0
	v_mul_f32_e32 v138, 0xbfb8aa3b, v136
	v_mul_f32_e32 v139, 0xbfb8aa3b, v137
	v_exp_f32_e32 v138, v138
	v_exp_f32_e32 v139, v139
	v_add_f32_e32 v138, 1.0, v138
	v_add_f32_e32 v139, 1.0, v139
	v_rcp_f32_e32 v138, v138
	v_rcp_f32_e32 v139, v139
	s_nop 0
	v_pk_mul_f32 v[136:137], v[136:137], v[138:139]
	s_nop 0
	v_pk_mul_f32 v[134:135], v[134:135], v[136:137]
	v_lshlrev_b32_e32 v136, 16, v145
	v_and_b32_e32 v137, 0xffff0000, v145
	v_pk_mul_f32 v[136:137], v[100:101], v[136:137]
	v_lshlrev_b32_e32 v138, 16, v150
	v_and_b32_e32 v139, 0xffff0000, v150
	v_pk_fma_f32 v[136:137], v[92:93], v[140:141], v[136:137]
	v_lshlrev_b32_e32 v140, 16, v155
	v_pk_fma_f32 v[136:137], v[88:89], v[138:139], v[136:137]
	v_and_b32_e32 v141, 0xffff0000, v155
	v_pk_add_f32 v[136:137], v[96:97], v[136:137]
	s_nop 0
	v_mul_f32_e32 v138, 0xbfb8aa3b, v136
	v_mul_f32_e32 v139, 0xbfb8aa3b, v137
	v_exp_f32_e32 v138, v138
	v_exp_f32_e32 v139, v139
	v_add_f32_e32 v138, 1.0, v138
	v_add_f32_e32 v139, 1.0, v139
	v_rcp_f32_e32 v138, v138
	v_rcp_f32_e32 v139, v139
	s_nop 0
	v_pk_mul_f32 v[136:137], v[136:137], v[138:139]
	s_nop 0
	v_pk_mul_f32 v[136:137], v[128:129], v[136:137]
	v_lshlrev_b32_e32 v128, 16, v151
	v_and_b32_e32 v129, 0xffff0000, v151
	v_pk_mul_f32 v[128:129], v[102:103], v[128:129]
	v_lshlrev_b32_e32 v138, 16, v158
	v_and_b32_e32 v139, 0xffff0000, v158
	v_pk_fma_f32 v[128:129], v[94:95], v[140:141], v[128:129]
	s_nop 0
	v_pk_fma_f32 v[128:129], v[90:91], v[138:139], v[128:129]
	s_nop 0
	v_pk_add_f32 v[128:129], v[98:99], v[128:129]
	s_nop 0
	v_mul_f32_e32 v138, 0xbfb8aa3b, v128
	v_mul_f32_e32 v139, 0xbfb8aa3b, v129
	v_exp_f32_e32 v138, v138
	v_exp_f32_e32 v139, v139
	v_add_f32_e32 v138, 1.0, v138
	v_add_f32_e32 v139, 1.0, v139
	v_rcp_f32_e32 v138, v138
	v_rcp_f32_e32 v139, v139
	s_nop 0
	v_pk_mul_f32 v[128:129], v[128:129], v[138:139]
	s_nop 0
	v_pk_mul_f32 v[138:139], v[130:131], v[128:129]
	v_cvt_pk_bf16_f32 v128, v132, v133
	v_mad_i64_i32 v[132:133], s[2:3], v142, s26, v[172:173]
	v_cvt_pk_bf16_f32 v129, v134, v135
	v_cvt_pk_bf16_f32 v130, v136, v137
	v_cvt_pk_bf16_f32 v131, v138, v139
	v_lshl_add_u64 v[144:145], v[132:133], 0, v[204:205]
	global_store_dwordx4 v[144:145], v[128:131], off
	s_nop 1
	v_mad_i64_i32 v[128:129], s[2:3], v164, s26, v[208:209]
	v_lshl_add_u64 v[150:151], v[128:129], 0, v[204:205]
	v_add_co_u32_e32 v152, vcc, s21, v150
	s_mul_hi_i32 s2, s12, 0x2c00
	s_nop 0
	v_addc_co_u32_e32 v153, vcc, 0, v151, vcc
	v_add_co_u32_e32 v154, vcc, s22, v150
	global_load_dwordx4 v[140:143], v[150:151], off
	global_load_dwordx4 v[136:139], v[152:153], off
	v_addc_co_u32_e32 v155, vcc, 0, v151, vcc
	v_add_co_u32_e32 v158, vcc, s23, v150
	s_cselect_b64 s[22:23], -1, 0
	s_add_i32 s1, s1, 0x160000
	s_add_u32 s0, s10, s1
	s_addc_u32 s1, s11, s2
	s_and_b64 s[2:3], s[22:23], exec
	v_addc_co_u32_e32 v159, vcc, 0, v151, vcc
	s_cselect_b32 s2, 0, 0xffffd400
	s_cselect_b32 s3, 0, -1
	s_cmp_eq_u32 s15, s13
	s_cselect_b64 vcc, -1, 0
	v_lshl_add_u64 v[160:161], s[0:1], 0, v[204:205]
	s_and_b64 s[0:1], vcc, exec
	s_cselect_b32 s72, 0, 0xb0000
	v_lshl_add_u64 v[162:163], v[160:161], 0, s[2:3]
	v_lshl_add_u64 v[160:161], v[160:161], 0, s[72:73]
	global_load_dwordx4 v[166:169], v[162:163], off
	global_load_dwordx4 v[226:229], v[160:161], off
	global_load_dwordx4 v[132:135], v[154:155], off
	global_load_dwordx4 v[128:131], v[158:159], off
	global_load_dword v253, v[150:151], off offset:256
	global_load_dword v253, v[152:153], off offset:256
	global_load_dword v253, v[162:163], off offset:256
	global_load_dword v253, v[160:161], off offset:256
	global_load_dword v253, v[154:155], off offset:256
	global_load_dword v253, v[158:159], off offset:256
	s_nop 0
	s_nop 0
	s_nop 0
	s_nop 0
	s_waitcnt vmcnt(5)
	ds_bpermute_b32 v175, v225, v140
	ds_bpermute_b32 v208, v225, v141
	ds_bpermute_b32 v209, v225, v142
	s_waitcnt vmcnt(4)
	ds_bpermute_b32 v231, v225, v136
	ds_bpermute_b32 v232, v225, v137
	ds_bpermute_b32 v233, v225, v138
	ds_bpermute_b32 v230, v225, v143
	ds_bpermute_b32 v234, v225, v139
	s_waitcnt lgkmcnt(4)
	v_cndmask_b32_e64 v175, v175, v231, s[6:7]
	s_waitcnt lgkmcnt(3)
	v_cndmask_b32_e64 v237, v208, v232, s[6:7]
	s_waitcnt lgkmcnt(2)
	v_cndmask_b32_e64 v239, v209, v233, s[6:7]
	v_lshlrev_b32_e32 v208, 16, v140
	v_and_b32_e32 v209, 0xffff0000, v140
	s_waitcnt lgkmcnt(0)
	v_cndmask_b32_e64 v230, v230, v234, s[6:7]
	s_waitcnt vmcnt(3)
	v_cndmask_b32_e64 v170, v168, 0, s[22:23]
	s_waitcnt vmcnt(2)
	v_cndmask_b32_e64 v168, v226, 0, vcc
	ds_bpermute_b32 v226, v193, v140
	v_cndmask_b32_e64 v171, v167, 0, s[22:23]
	v_cndmask_b32_e64 v174, v166, 0, s[22:23]
	v_cndmask_b32_e64 v166, v228, 0, vcc
	v_cndmask_b32_e64 v167, v227, 0, vcc
	ds_bpermute_b32 v227, v193, v141
	ds_bpermute_b32 v228, v193, v142
	s_waitcnt lgkmcnt(2)
	v_cndmask_b32_e64 v235, v226, v174, s[4:5]
	v_lshlrev_b32_e32 v174, 16, v175
	v_and_b32_e32 v175, 0xffff0000, v175
	s_waitcnt lgkmcnt(1)
	v_cndmask_b32_e64 v236, v227, v171, s[4:5]
	s_waitcnt lgkmcnt(0)
	v_cndmask_b32_e64 v238, v228, v170, s[4:5]
	v_lshlrev_b32_e32 v170, 16, v235
	v_and_b32_e32 v171, 0xffff0000, v235
	v_pk_mul_f32 v[170:171], v[120:121], v[170:171]
	v_cndmask_b32_e64 v165, v229, 0, vcc
	v_pk_fma_f32 v[170:171], v[112:113], v[208:209], v[170:171]
	ds_bpermute_b32 v229, v193, v143
	v_pk_fma_f32 v[170:171], v[108:109], v[174:175], v[170:171]
	v_cndmask_b32_e64 v169, v169, 0, s[22:23]
	v_pk_add_f32 v[170:171], v[116:117], v[170:171]
	s_waitcnt lgkmcnt(0)
	v_cndmask_b32_e64 v169, v229, v169, s[4:5]
	v_mul_f32_e32 v140, 0xbfb8aa3b, v170
	v_exp_f32_e32 v140, v140
	s_nop 0
	v_add_f32_e32 v140, 1.0, v140
	v_rcp_f32_e32 v174, v140
	v_mul_f32_e32 v140, 0xbfb8aa3b, v171
	v_exp_f32_e32 v140, v140
	s_nop 0
	v_add_f32_e32 v140, 1.0, v140
	v_rcp_f32_e32 v175, v140
	v_lshlrev_b32_e32 v140, 16, v141
	v_and_b32_e32 v141, 0xffff0000, v141
	v_pk_mul_f32 v[170:171], v[170:171], v[174:175]
	s_nop 0
	v_pk_mul_f32 v[124:125], v[124:125], v[170:171]
	v_lshlrev_b32_e32 v170, 16, v236
	v_and_b32_e32 v171, 0xffff0000, v236
	v_pk_mul_f32 v[170:171], v[122:123], v[170:171]
	v_lshlrev_b32_e32 v174, 16, v237
	v_and_b32_e32 v175, 0xffff0000, v237
	v_pk_fma_f32 v[140:141], v[114:115], v[140:141], v[170:171]
	s_nop 0
	v_pk_fma_f32 v[140:141], v[110:111], v[174:175], v[140:141]
	v_lshlrev_b32_e32 v174, 16, v142
	v_pk_add_f32 v[140:141], v[118:119], v[140:141]
	v_and_b32_e32 v175, 0xffff0000, v142
	v_mul_f32_e32 v170, 0xbfb8aa3b, v140
	v_mul_f32_e32 v171, 0xbfb8aa3b, v141
	v_exp_f32_e32 v170, v170
	v_exp_f32_e32 v171, v171
	v_add_f32_e32 v170, 1.0, v170
	v_add_f32_e32 v171, 1.0, v171
	v_rcp_f32_e32 v170, v170
	v_rcp_f32_e32 v171, v171
	s_nop 0
	v_pk_mul_f32 v[140:141], v[140:141], v[170:171]
	s_nop 0
	v_pk_mul_f32 v[126:127], v[126:127], v[140:141]
	v_lshlrev_b32_e32 v140, 16, v238
	v_and_b32_e32 v141, 0xffff0000, v238
	v_pk_mul_f32 v[140:141], v[100:101], v[140:141]
	v_lshlrev_b32_e32 v170, 16, v239
	v_and_b32_e32 v171, 0xffff0000, v239
	v_pk_fma_f32 v[140:141], v[92:93], v[174:175], v[140:141]
	s_waitcnt vmcnt(1)
	ds_bpermute_b32 v174, v225, v134
	v_pk_fma_f32 v[140:141], v[88:89], v[170:171], v[140:141]
	ds_bpermute_b32 v175, v225, v135
	v_pk_add_f32 v[140:141], v[96:97], v[140:141]
	s_nop 0
	v_mul_f32_e32 v142, 0xbfb8aa3b, v140
	v_exp_f32_e32 v142, v142
	s_nop 0
	v_add_f32_e32 v142, 1.0, v142
	v_rcp_f32_e32 v170, v142
	v_mul_f32_e32 v142, 0xbfb8aa3b, v141
	v_exp_f32_e32 v142, v142
	s_nop 0
	v_add_f32_e32 v142, 1.0, v142
	v_rcp_f32_e32 v171, v142
	v_lshlrev_b32_e32 v142, 16, v143
	v_and_b32_e32 v143, 0xffff0000, v143
	v_pk_mul_f32 v[140:141], v[140:141], v[170:171]
	s_nop 0
	v_pk_mul_f32 v[140:141], v[104:105], v[140:141]
	v_lshlrev_b32_e32 v104, 16, v169
	v_and_b32_e32 v105, 0xffff0000, v169
	v_pk_mul_f32 v[104:105], v[102:103], v[104:105]
	v_lshlrev_b32_e32 v170, 16, v230
	v_and_b32_e32 v171, 0xffff0000, v230
	v_pk_fma_f32 v[104:105], v[94:95], v[142:143], v[104:105]
	v_or_b32_e32 v169, 16, v164
	v_pk_fma_f32 v[104:105], v[90:91], v[170:171], v[104:105]
	ds_bpermute_b32 v170, v225, v132
	v_pk_add_f32 v[104:105], v[98:99], v[104:105]
	ds_bpermute_b32 v171, v225, v133
	v_mul_f32_e32 v142, 0xbfb8aa3b, v104
	v_mul_f32_e32 v143, 0xbfb8aa3b, v105
	v_exp_f32_e32 v142, v142
	v_exp_f32_e32 v143, v143
	s_waitcnt lgkmcnt(0)
	v_cndmask_b32_e64 v209, v232, v171, s[6:7]
	v_add_f32_e32 v142, 1.0, v142
	v_add_f32_e32 v143, 1.0, v143
	v_rcp_f32_e32 v142, v142
	v_rcp_f32_e32 v143, v143
	s_nop 0
	v_pk_mul_f32 v[104:105], v[104:105], v[142:143]
	s_nop 0
	v_pk_mul_f32 v[142:143], v[106:107], v[104:105]
	v_cvt_pk_bf16_f32 v106, v140, v141
	ds_bpermute_b32 v140, v193, v136
	v_cvt_pk_bf16_f32 v104, v124, v125
	v_mad_i64_i32 v[124:125], s[0:1], v164, s26, v[172:173]
	v_cvt_pk_bf16_f32 v105, v126, v127
	v_cvt_pk_bf16_f32 v107, v142, v143
	v_lshl_add_u64 v[124:125], v[124:125], 0, v[204:205]
	global_store_dwordx4 v[124:125], v[104:107], off
	v_lshlrev_b32_e32 v126, 16, v136
	v_and_b32_e32 v127, 0xffff0000, v136
	s_waitcnt lgkmcnt(0)
	v_cndmask_b32_e64 v105, v140, v226, s[4:5]
	v_lshlrev_b32_e32 v104, 16, v105
	v_and_b32_e32 v105, 0xffff0000, v105
	v_cndmask_b32_e64 v107, v231, v170, s[6:7]
	v_pk_mul_f32 v[104:105], v[120:121], v[104:105]
	v_lshlrev_b32_e32 v106, 16, v107
	v_and_b32_e32 v107, 0xffff0000, v107
	v_pk_fma_f32 v[104:105], v[112:113], v[126:127], v[104:105]
	ds_bpermute_b32 v141, v193, v137
	v_pk_fma_f32 v[104:105], v[108:109], v[106:107], v[104:105]
	v_lshlrev_b32_e32 v126, 16, v137
	v_pk_add_f32 v[104:105], v[116:117], v[104:105]
	v_and_b32_e32 v127, 0xffff0000, v137
	v_mul_f32_e32 v106, 0xbfb8aa3b, v104
	v_mul_f32_e32 v107, 0xbfb8aa3b, v105
	v_exp_f32_e32 v106, v106
	v_exp_f32_e32 v107, v107
	s_waitcnt lgkmcnt(0)
	v_cndmask_b32_e64 v208, v141, v227, s[4:5]
	ds_bpermute_b32 v142, v193, v138
	v_add_f32_e32 v106, 1.0, v106
	v_add_f32_e32 v107, 1.0, v107
	v_rcp_f32_e32 v106, v106
	v_rcp_f32_e32 v107, v107
	s_waitcnt lgkmcnt(0)
	v_cndmask_b32_e64 v226, v142, v228, s[4:5]
	v_cndmask_b32_e64 v227, v233, v174, s[6:7]
	ds_bpermute_b32 v143, v193, v139
	v_pk_mul_f32 v[104:105], v[104:105], v[106:107]
	v_lshlrev_b32_e32 v106, 16, v209
	v_pk_mul_f32 v[84:85], v[84:85], v[104:105]
	v_lshlrev_b32_e32 v104, 16, v208
	v_and_b32_e32 v105, 0xffff0000, v208
	v_pk_mul_f32 v[104:105], v[122:123], v[104:105]
	v_and_b32_e32 v107, 0xffff0000, v209
	v_pk_fma_f32 v[104:105], v[114:115], v[126:127], v[104:105]
	v_lshlrev_b32_e32 v126, 16, v138
	v_pk_fma_f32 v[104:105], v[110:111], v[106:107], v[104:105]
	v_and_b32_e32 v127, 0xffff0000, v138
	v_pk_add_f32 v[104:105], v[118:119], v[104:105]
	s_waitcnt lgkmcnt(0)
	v_cndmask_b32_e64 v228, v143, v229, s[4:5]
	v_mul_f32_e32 v106, 0xbfb8aa3b, v104
	v_mul_f32_e32 v107, 0xbfb8aa3b, v105
	v_exp_f32_e32 v106, v106
	v_exp_f32_e32 v107, v107
	v_cndmask_b32_e64 v229, v234, v175, s[6:7]
	s_waitcnt vmcnt(1)
	ds_bpermute_b32 v136, v225, v129
	v_add_f32_e32 v106, 1.0, v106
	v_add_f32_e32 v107, 1.0, v107
	v_rcp_f32_e32 v106, v106
	v_rcp_f32_e32 v107, v107
	ds_bpermute_b32 v137, v225, v130
	ds_bpermute_b32 v138, v225, v131
	v_pk_mul_f32 v[104:105], v[104:105], v[106:107]
	s_nop 0
	v_pk_mul_f32 v[86:87], v[86:87], v[104:105]
	v_lshlrev_b32_e32 v104, 16, v226
	v_and_b32_e32 v105, 0xffff0000, v226
	v_pk_mul_f32 v[104:105], v[100:101], v[104:105]
	v_lshlrev_b32_e32 v106, 16, v227
	v_and_b32_e32 v107, 0xffff0000, v227
	v_pk_fma_f32 v[104:105], v[92:93], v[126:127], v[104:105]
	v_lshlrev_b32_e32 v126, 16, v139
	v_pk_fma_f32 v[104:105], v[88:89], v[106:107], v[104:105]
	v_and_b32_e32 v127, 0xffff0000, v139
	v_pk_add_f32 v[104:105], v[96:97], v[104:105]
	s_nop 0
	v_mul_f32_e32 v106, 0xbfb8aa3b, v104
	v_mul_f32_e32 v107, 0xbfb8aa3b, v105
	v_exp_f32_e32 v106, v106
	v_exp_f32_e32 v107, v107
	v_add_f32_e32 v106, 1.0, v106
	v_add_f32_e32 v107, 1.0, v107
	v_rcp_f32_e32 v106, v106
	v_rcp_f32_e32 v107, v107
	s_nop 0
	v_pk_mul_f32 v[104:105], v[104:105], v[106:107]
	s_nop 0
	v_pk_mul_f32 v[104:105], v[80:81], v[104:105]
	v_lshlrev_b32_e32 v80, 16, v228
	v_and_b32_e32 v81, 0xffff0000, v228
	v_pk_mul_f32 v[80:81], v[102:103], v[80:81]
	v_lshlrev_b32_e32 v106, 16, v229
	v_and_b32_e32 v107, 0xffff0000, v229
	v_pk_fma_f32 v[80:81], v[94:95], v[126:127], v[80:81]
	s_nop 0
	v_pk_fma_f32 v[80:81], v[90:91], v[106:107], v[80:81]
	s_nop 0
	v_pk_add_f32 v[80:81], v[98:99], v[80:81]
	s_nop 0
	v_mul_f32_e32 v106, 0xbfb8aa3b, v80
	v_mul_f32_e32 v107, 0xbfb8aa3b, v81
	v_exp_f32_e32 v106, v106
	v_exp_f32_e32 v107, v107
	v_add_f32_e32 v106, 1.0, v106
	v_add_f32_e32 v107, 1.0, v107
	v_rcp_f32_e32 v106, v106
	v_rcp_f32_e32 v107, v107
	s_nop 0
	v_pk_mul_f32 v[80:81], v[80:81], v[106:107]
	s_nop 0
	v_pk_mul_f32 v[106:107], v[82:83], v[80:81]
	v_cvt_pk_bf16_f32 v81, v86, v87
	ds_bpermute_b32 v86, v193, v132
	v_cvt_pk_bf16_f32 v83, v106, v107
	ds_bpermute_b32 v107, v225, v128
	v_cvt_pk_bf16_f32 v80, v84, v85
	v_mad_i64_i32 v[84:85], s[0:1], v169, s26, v[172:173]
	v_cvt_pk_bf16_f32 v82, v104, v105
	v_lshl_add_u64 v[126:127], v[84:85], 0, v[204:205]
	global_store_dwordx4 v[126:127], v[80:83], off
	v_lshlrev_b32_e32 v84, 16, v132
	v_and_b32_e32 v85, 0xffff0000, v132
	s_waitcnt lgkmcnt(1)
	v_cndmask_b32_e64 v81, v86, v140, s[4:5]
	v_lshlrev_b32_e32 v80, 16, v81
	v_and_b32_e32 v81, 0xffff0000, v81
	s_waitcnt lgkmcnt(0)
	v_cndmask_b32_e64 v83, v170, v107, s[6:7]
	v_pk_mul_f32 v[80:81], v[120:121], v[80:81]
	v_lshlrev_b32_e32 v82, 16, v83
	v_and_b32_e32 v83, 0xffff0000, v83
	v_pk_fma_f32 v[80:81], v[112:113], v[84:85], v[80:81]
	ds_bpermute_b32 v87, v193, v133
	v_pk_fma_f32 v[80:81], v[108:109], v[82:83], v[80:81]
	v_cndmask_b32_e64 v140, v171, v136, s[6:7]
	v_pk_add_f32 v[80:81], v[116:117], v[80:81]
	v_lshlrev_b32_e32 v84, 16, v133
	v_mul_f32_e32 v82, 0xbfb8aa3b, v80
	v_mul_f32_e32 v83, 0xbfb8aa3b, v81
	v_exp_f32_e32 v82, v82
	v_exp_f32_e32 v83, v83
	s_waitcnt lgkmcnt(0)
	v_cndmask_b32_e64 v139, v87, v141, s[4:5]
	v_and_b32_e32 v85, 0xffff0000, v133
	v_add_f32_e32 v82, 1.0, v82
	v_add_f32_e32 v83, 1.0, v83
	v_rcp_f32_e32 v82, v82
	v_rcp_f32_e32 v83, v83
	ds_bpermute_b32 v104, v193, v134
	ds_bpermute_b32 v105, v193, v135
	v_cndmask_b32_e64 v169, v175, v138, s[6:7]
	v_pk_mul_f32 v[80:81], v[80:81], v[82:83]
	v_lshlrev_b32_e32 v82, 16, v140
	v_pk_mul_f32 v[76:77], v[76:77], v[80:81]
	v_lshlrev_b32_e32 v80, 16, v139
	v_and_b32_e32 v81, 0xffff0000, v139
	v_pk_mul_f32 v[80:81], v[122:123], v[80:81]
	v_and_b32_e32 v83, 0xffff0000, v140
	v_pk_fma_f32 v[80:81], v[114:115], v[84:85], v[80:81]
	s_waitcnt lgkmcnt(1)
	v_cndmask_b32_e64 v141, v104, v142, s[4:5]
	v_pk_fma_f32 v[80:81], v[110:111], v[82:83], v[80:81]
	v_cndmask_b32_e64 v142, v174, v137, s[6:7]
	v_pk_add_f32 v[80:81], v[118:119], v[80:81]
	v_lshlrev_b32_e32 v84, 16, v134
	v_mul_f32_e32 v82, 0xbfb8aa3b, v80
	v_mul_f32_e32 v83, 0xbfb8aa3b, v81
	v_exp_f32_e32 v82, v82
	v_exp_f32_e32 v83, v83
	v_and_b32_e32 v85, 0xffff0000, v134
	s_waitcnt lgkmcnt(0)
	v_cndmask_b32_e64 v143, v105, v143, s[4:5]
	v_add_f32_e32 v82, 1.0, v82
	v_add_f32_e32 v83, 1.0, v83
	v_rcp_f32_e32 v82, v82
	v_rcp_f32_e32 v83, v83
	v_or_b32_e32 v106, 32, v164
	v_pk_mul_f32 v[80:81], v[80:81], v[82:83]
	s_nop 0
	v_pk_mul_f32 v[78:79], v[78:79], v[80:81]
	v_lshlrev_b32_e32 v80, 16, v141
	v_and_b32_e32 v81, 0xffff0000, v141
	v_pk_mul_f32 v[80:81], v[100:101], v[80:81]
	v_lshlrev_b32_e32 v82, 16, v142
	v_and_b32_e32 v83, 0xffff0000, v142
	v_pk_fma_f32 v[80:81], v[92:93], v[84:85], v[80:81]
	v_lshlrev_b32_e32 v84, 16, v135
	v_pk_fma_f32 v[80:81], v[88:89], v[82:83], v[80:81]
	v_and_b32_e32 v85, 0xffff0000, v135
	v_pk_add_f32 v[80:81], v[96:97], v[80:81]
	s_nop 0
	v_mul_f32_e32 v82, 0xbfb8aa3b, v80
	v_mul_f32_e32 v83, 0xbfb8aa3b, v81
	v_exp_f32_e32 v82, v82
	v_exp_f32_e32 v83, v83
	v_add_f32_e32 v82, 1.0, v82
	v_add_f32_e32 v83, 1.0, v83
	v_rcp_f32_e32 v82, v82
	v_rcp_f32_e32 v83, v83
	s_nop 0
	v_pk_mul_f32 v[80:81], v[80:81], v[82:83]
	s_nop 0
	v_pk_mul_f32 v[80:81], v[72:73], v[80:81]
	v_lshlrev_b32_e32 v72, 16, v143
	v_and_b32_e32 v73, 0xffff0000, v143
	v_pk_mul_f32 v[72:73], v[102:103], v[72:73]
	v_lshlrev_b32_e32 v82, 16, v169
	v_and_b32_e32 v83, 0xffff0000, v169
	v_pk_fma_f32 v[72:73], v[94:95], v[84:85], v[72:73]
	v_cndmask_b32_e64 v84, v138, v165, s[6:7]
	v_pk_fma_f32 v[72:73], v[90:91], v[82:83], v[72:73]
	s_nop 0
	v_pk_add_f32 v[72:73], v[98:99], v[72:73]
	s_nop 0
	v_mul_f32_e32 v82, 0xbfb8aa3b, v72
	v_mul_f32_e32 v83, 0xbfb8aa3b, v73
	v_exp_f32_e32 v82, v82
	v_exp_f32_e32 v83, v83
	v_add_f32_e32 v82, 1.0, v82
	v_add_f32_e32 v83, 1.0, v83
	v_rcp_f32_e32 v82, v82
	v_rcp_f32_e32 v83, v83
	s_nop 0
	v_pk_mul_f32 v[72:73], v[72:73], v[82:83]
	s_nop 0
	v_pk_mul_f32 v[82:83], v[74:75], v[72:73]
	v_cvt_pk_bf16_f32 v72, v76, v77
	v_mad_i64_i32 v[76:77], s[0:1], v106, s26, v[172:173]
	v_cvt_pk_bf16_f32 v73, v78, v79
	v_cvt_pk_bf16_f32 v74, v80, v81
	v_cvt_pk_bf16_f32 v75, v82, v83
	v_lshl_add_u64 v[132:133], v[76:77], 0, v[204:205]
	global_store_dwordx4 v[132:133], v[72:75], off
	ds_bpermute_b32 v72, v193, v128
	ds_bpermute_b32 v73, v193, v129
	ds_bpermute_b32 v74, v193, v130
	ds_bpermute_b32 v75, v193, v131
	v_cndmask_b32_e64 v77, v107, v168, s[6:7]
	s_waitcnt lgkmcnt(3)
	v_cndmask_b32_e64 v76, v72, v86, s[4:5]
	s_waitcnt lgkmcnt(2)
	v_cndmask_b32_e64 v79, v73, v87, s[4:5]
	v_lshlrev_b32_e32 v72, 16, v76
	v_and_b32_e32 v73, 0xffff0000, v76
	s_waitcnt lgkmcnt(1)
	v_cndmask_b32_e64 v81, v74, v104, s[4:5]
	s_waitcnt lgkmcnt(0)
	v_cndmask_b32_e64 v83, v75, v105, s[4:5]
	v_lshlrev_b32_e32 v74, 16, v77
	v_and_b32_e32 v75, 0xffff0000, v77
	v_pk_mul_f32 v[72:73], v[120:121], v[72:73]
	v_lshlrev_b32_e32 v76, 16, v128
	v_and_b32_e32 v77, 0xffff0000, v128
	v_pk_fma_f32 v[72:73], v[112:113], v[76:77], v[72:73]
	v_cndmask_b32_e64 v80, v136, v167, s[6:7]
	v_pk_fma_f32 v[72:73], v[108:109], v[74:75], v[72:73]
	v_lshlrev_b32_e32 v76, 16, v129
	v_pk_add_f32 v[72:73], v[116:117], v[72:73]
	v_and_b32_e32 v77, 0xffff0000, v129
	v_mul_f32_e32 v74, 0xbfb8aa3b, v72
	v_mul_f32_e32 v75, 0xbfb8aa3b, v73
	v_exp_f32_e32 v74, v74
	v_exp_f32_e32 v75, v75
	v_cndmask_b32_e64 v82, v137, v166, s[6:7]
	v_or_b32_e32 v78, 48, v164
	v_add_f32_e32 v74, 1.0, v74
	v_add_f32_e32 v75, 1.0, v75
	v_rcp_f32_e32 v74, v74
	v_rcp_f32_e32 v75, v75
	s_nop 0
	v_pk_mul_f32 v[72:73], v[72:73], v[74:75]
	s_nop 0
	v_pk_mul_f32 v[68:69], v[68:69], v[72:73]
	v_lshlrev_b32_e32 v72, 16, v79
	v_and_b32_e32 v73, 0xffff0000, v79
	v_pk_mul_f32 v[72:73], v[122:123], v[72:73]
	v_lshlrev_b32_e32 v74, 16, v80
	v_and_b32_e32 v75, 0xffff0000, v80
	v_pk_fma_f32 v[72:73], v[114:115], v[76:77], v[72:73]
	v_lshlrev_b32_e32 v76, 16, v130
	v_pk_fma_f32 v[72:73], v[110:111], v[74:75], v[72:73]
	v_and_b32_e32 v77, 0xffff0000, v130
	v_pk_add_f32 v[72:73], v[118:119], v[72:73]
	s_nop 0
	v_mul_f32_e32 v74, 0xbfb8aa3b, v72
	v_mul_f32_e32 v75, 0xbfb8aa3b, v73
	v_exp_f32_e32 v74, v74
	v_exp_f32_e32 v75, v75
	v_add_f32_e32 v74, 1.0, v74
	v_add_f32_e32 v75, 1.0, v75
	v_rcp_f32_e32 v74, v74
	v_rcp_f32_e32 v75, v75
	s_nop 0
	v_pk_mul_f32 v[72:73], v[72:73], v[74:75]
	s_nop 0
	v_pk_mul_f32 v[70:71], v[70:71], v[72:73]
	v_lshlrev_b32_e32 v72, 16, v81
	v_and_b32_e32 v73, 0xffff0000, v81
	v_pk_mul_f32 v[72:73], v[100:101], v[72:73]
	v_lshlrev_b32_e32 v74, 16, v82
	v_and_b32_e32 v75, 0xffff0000, v82
	v_pk_fma_f32 v[72:73], v[92:93], v[76:77], v[72:73]
	v_lshlrev_b32_e32 v76, 16, v131
	v_pk_fma_f32 v[72:73], v[88:89], v[74:75], v[72:73]
	v_and_b32_e32 v77, 0xffff0000, v131
	v_pk_add_f32 v[72:73], v[96:97], v[72:73]
	s_nop 0
	v_mul_f32_e32 v74, 0xbfb8aa3b, v72
	v_mul_f32_e32 v75, 0xbfb8aa3b, v73
	v_exp_f32_e32 v74, v74
	v_exp_f32_e32 v75, v75
	v_add_f32_e32 v74, 1.0, v74
	v_add_f32_e32 v75, 1.0, v75
	v_rcp_f32_e32 v74, v74
	v_rcp_f32_e32 v75, v75
	s_nop 0
	v_pk_mul_f32 v[72:73], v[72:73], v[74:75]
	s_nop 0
	v_pk_mul_f32 v[72:73], v[64:65], v[72:73]
	v_lshlrev_b32_e32 v64, 16, v83
	v_and_b32_e32 v65, 0xffff0000, v83
	v_pk_mul_f32 v[64:65], v[102:103], v[64:65]
	v_lshlrev_b32_e32 v74, 16, v84
	v_and_b32_e32 v75, 0xffff0000, v84
	v_pk_fma_f32 v[64:65], v[94:95], v[76:77], v[64:65]
	s_nop 0
	v_pk_fma_f32 v[64:65], v[90:91], v[74:75], v[64:65]
	s_nop 0
	v_pk_add_f32 v[64:65], v[98:99], v[64:65]
	s_nop 0
	v_mul_f32_e32 v74, 0xbfb8aa3b, v64
	v_mul_f32_e32 v75, 0xbfb8aa3b, v65
	v_exp_f32_e32 v74, v74
	v_exp_f32_e32 v75, v75
	v_add_f32_e32 v74, 1.0, v74
	v_add_f32_e32 v75, 1.0, v75
	v_rcp_f32_e32 v74, v74
	v_rcp_f32_e32 v75, v75
	s_nop 0
	v_pk_mul_f32 v[64:65], v[64:65], v[74:75]
	s_nop 0
	v_pk_mul_f32 v[74:75], v[66:67], v[64:65]
	v_cvt_pk_bf16_f32 v64, v68, v69
	v_mad_i64_i32 v[68:69], s[0:1], v78, s26, v[172:173]
	v_cvt_pk_bf16_f32 v65, v70, v71
	v_cvt_pk_bf16_f32 v66, v72, v73
	v_cvt_pk_bf16_f32 v67, v74, v75
	v_lshl_add_u64 v[112:113], v[68:69], 0, v[204:205]
	global_store_dwordx4 v[112:113], v[64:67], off
	s_mov_b64 s[0:1], -1
	s_nop 0
	v_or_b32_e32 v64, 0x80, v192
	v_ashrrev_i32_e32 v65, 31, v64
	v_lshlrev_b64 v[64:65], 2, v[64:65]
	v_lshl_add_u64 v[66:67], s[46:47], 0, v[64:65]
	v_lshl_add_u64 v[72:73], s[48:49], 0, v[64:65]
	global_load_dwordx4 v[76:79], v[190:191], off offset:528
	global_load_dwordx4 v[92:95], v[190:191], off offset:512
	global_load_dwordx4 v[68:71], v[66:67], off offset:16
	global_load_dwordx4 v[84:87], v[66:67], off
	s_nop 0
	global_load_dwordx4 v[64:67], v[72:73], off offset:16
	global_load_dwordx4 v[80:83], v[72:73], off
	s_nop 0
	global_load_dwordx4 v[72:75], v[188:189], off offset:528
	global_load_dwordx4 v[88:91], v[188:189], off offset:512
	global_load_dwordx4 v[108:111], v[194:195], off offset:256
	global_load_dwordx4 v[104:107], v[198:199], off offset:256
	global_load_dwordx4 v[100:103], v[200:201], off offset:256
	global_load_dwordx4 v[96:99], v[206:207], off offset:256
	global_load_dwordx4 v[114:117], v[196:197], off offset:256
	global_load_dwordx4 v[118:121], v[202:203], off offset:256
	s_waitcnt vmcnt(5)
	ds_bpermute_b32 v130, v193, v108
	s_waitcnt vmcnt(4)
	ds_bpermute_b32 v136, v225, v104
	ds_bpermute_b32 v137, v225, v105
	ds_bpermute_b32 v134, v193, v110
	s_waitcnt vmcnt(1)
	v_cndmask_b32_e64 v122, v117, 0, s[62:63]
	v_cndmask_b32_e64 v123, v116, 0, s[62:63]
	s_waitcnt vmcnt(0)
	v_cndmask_b32_e64 v116, v119, 0, s[50:51]
	v_cndmask_b32_e64 v117, v118, 0, s[50:51]
	ds_bpermute_b32 v118, v225, v108
	ds_bpermute_b32 v119, v225, v109
	ds_bpermute_b32 v135, v193, v111
	v_cndmask_b32_e64 v128, v115, 0, s[62:63]
	v_cndmask_b32_e64 v129, v114, 0, s[62:63]
	v_cndmask_b32_e64 v114, v121, 0, s[50:51]
	v_cndmask_b32_e64 v115, v120, 0, s[50:51]
	ds_bpermute_b32 v120, v225, v110
	ds_bpermute_b32 v121, v225, v111
	ds_bpermute_b32 v138, v225, v106
	ds_bpermute_b32 v139, v225, v107
	s_waitcnt lgkmcnt(10)
	v_cndmask_b32_e64 v129, v130, v129, s[4:5]
	s_waitcnt lgkmcnt(6)
	v_cndmask_b32_e64 v140, v118, v136, s[6:7]
	s_waitcnt lgkmcnt(5)
	v_cndmask_b32_e64 v141, v119, v137, s[6:7]
	v_lshlrev_b32_e32 v118, 16, v129
	v_and_b32_e32 v119, 0xffff0000, v129
	v_cndmask_b32_e64 v142, v134, v123, s[4:5]
	s_waitcnt lgkmcnt(4)
	v_cndmask_b32_e64 v164, v135, v122, s[4:5]
	v_pk_mul_f32 v[118:119], v[92:93], v[118:119]
	v_lshlrev_b32_e32 v122, 16, v108
	v_and_b32_e32 v123, 0xffff0000, v108
	s_waitcnt lgkmcnt(1)
	v_cndmask_b32_e64 v143, v120, v138, s[6:7]
	s_waitcnt lgkmcnt(0)
	v_cndmask_b32_e64 v165, v121, v139, s[6:7]
	v_lshlrev_b32_e32 v120, 16, v140
	v_and_b32_e32 v121, 0xffff0000, v140
	v_pk_fma_f32 v[118:119], v[84:85], v[122:123], v[118:119]
	ds_bpermute_b32 v131, v193, v109
	v_pk_fma_f32 v[118:119], v[80:81], v[120:121], v[118:119]
	s_waitcnt lgkmcnt(0)
	v_cndmask_b32_e64 v128, v131, v128, s[4:5]
	v_pk_add_f32 v[118:119], v[88:89], v[118:119]
	s_nop 0
	v_mul_f32_e32 v108, 0xbfb8aa3b, v118
	v_exp_f32_e32 v108, v108
	s_nop 0
	v_add_f32_e32 v108, 1.0, v108
	v_rcp_f32_e32 v120, v108
	v_mul_f32_e32 v108, 0xbfb8aa3b, v119
	v_exp_f32_e32 v108, v108
	s_nop 0
	v_add_f32_e32 v108, 1.0, v108
	v_rcp_f32_e32 v121, v108
	v_lshlrev_b32_e32 v108, 16, v109
	v_and_b32_e32 v109, 0xffff0000, v109
	v_pk_mul_f32 v[118:119], v[118:119], v[120:121]
	s_nop 0
	v_pk_mul_f32 v[60:61], v[60:61], v[118:119]
	v_lshlrev_b32_e32 v118, 16, v128
	v_and_b32_e32 v119, 0xffff0000, v128
	v_pk_mul_f32 v[118:119], v[94:95], v[118:119]
	v_lshlrev_b32_e32 v120, 16, v141
	v_and_b32_e32 v121, 0xffff0000, v141
	v_pk_fma_f32 v[108:109], v[86:87], v[108:109], v[118:119]
	s_nop 0
	v_pk_fma_f32 v[108:109], v[82:83], v[120:121], v[108:109]
	v_lshlrev_b32_e32 v120, 16, v110
	v_pk_add_f32 v[108:109], v[90:91], v[108:109]
	v_and_b32_e32 v121, 0xffff0000, v110
	v_mul_f32_e32 v118, 0xbfb8aa3b, v108
	v_mul_f32_e32 v119, 0xbfb8aa3b, v109
	v_exp_f32_e32 v118, v118
	v_exp_f32_e32 v119, v119
	v_add_f32_e32 v118, 1.0, v118
	v_add_f32_e32 v119, 1.0, v119
	v_rcp_f32_e32 v118, v118
	v_rcp_f32_e32 v119, v119
	s_nop 0
	v_pk_mul_f32 v[108:109], v[108:109], v[118:119]
	s_nop 0
	v_pk_mul_f32 v[62:63], v[62:63], v[108:109]
	v_lshlrev_b32_e32 v108, 16, v142
	v_and_b32_e32 v109, 0xffff0000, v142
	v_pk_mul_f32 v[108:109], v[76:77], v[108:109]
	v_lshlrev_b32_e32 v118, 16, v143
	v_and_b32_e32 v119, 0xffff0000, v143
	v_pk_fma_f32 v[108:109], v[68:69], v[120:121], v[108:109]
	s_nop 0
	v_pk_fma_f32 v[108:109], v[64:65], v[118:119], v[108:109]
	s_nop 0
	v_pk_add_f32 v[108:109], v[72:73], v[108:109]
	s_nop 0
	v_mul_f32_e32 v110, 0xbfb8aa3b, v108
	v_exp_f32_e32 v110, v110
	s_nop 0
	v_add_f32_e32 v110, 1.0, v110
	v_rcp_f32_e32 v118, v110
	v_mul_f32_e32 v110, 0xbfb8aa3b, v109
	v_exp_f32_e32 v110, v110
	s_nop 0
	v_add_f32_e32 v110, 1.0, v110
	v_rcp_f32_e32 v119, v110
	v_lshlrev_b32_e32 v110, 16, v111
	v_and_b32_e32 v111, 0xffff0000, v111
	v_pk_mul_f32 v[108:109], v[108:109], v[118:119]
	s_nop 0
	v_pk_mul_f32 v[108:109], v[56:57], v[108:109]
	v_lshlrev_b32_e32 v56, 16, v164
	v_and_b32_e32 v57, 0xffff0000, v164
	v_pk_mul_f32 v[56:57], v[78:79], v[56:57]
	v_lshlrev_b32_e32 v118, 16, v165
	v_and_b32_e32 v119, 0xffff0000, v165
	v_pk_fma_f32 v[56:57], v[70:71], v[110:111], v[56:57]
	s_nop 0
	v_pk_fma_f32 v[56:57], v[66:67], v[118:119], v[56:57]
	ds_bpermute_b32 v118, v225, v102
	v_pk_add_f32 v[56:57], v[74:75], v[56:57]
	ds_bpermute_b32 v119, v225, v103
	v_mul_f32_e32 v110, 0xbfb8aa3b, v56
	v_mul_f32_e32 v111, 0xbfb8aa3b, v57
	v_exp_f32_e32 v110, v110
	v_exp_f32_e32 v111, v111
	s_waitcnt lgkmcnt(1)
	v_cndmask_b32_e64 v123, v138, v118, s[6:7]
	s_waitcnt lgkmcnt(0)
	v_cndmask_b32_e64 v129, v139, v119, s[6:7]
	v_add_f32_e32 v110, 1.0, v110
	v_add_f32_e32 v111, 1.0, v111
	v_rcp_f32_e32 v110, v110
	v_rcp_f32_e32 v111, v111
	s_nop 0
	v_pk_mul_f32 v[56:57], v[56:57], v[110:111]
	s_nop 0
	v_pk_mul_f32 v[110:111], v[58:59], v[56:57]
	v_cvt_pk_bf16_f32 v57, v62, v63
	ds_bpermute_b32 v62, v193, v104
	v_cvt_pk_bf16_f32 v59, v110, v111
	ds_bpermute_b32 v110, v225, v100
	v_cvt_pk_bf16_f32 v56, v60, v61
	v_cvt_pk_bf16_f32 v58, v108, v109
	global_store_dwordx4 v[156:157], v[56:59], off offset:256
	v_lshlrev_b32_e32 v60, 16, v104
	v_and_b32_e32 v61, 0xffff0000, v104
	s_waitcnt lgkmcnt(1)
	v_cndmask_b32_e64 v57, v62, v130, s[4:5]
	v_lshlrev_b32_e32 v56, 16, v57
	v_and_b32_e32 v57, 0xffff0000, v57
	s_waitcnt lgkmcnt(0)
	v_cndmask_b32_e64 v59, v136, v110, s[6:7]
	v_pk_mul_f32 v[56:57], v[92:93], v[56:57]
	v_lshlrev_b32_e32 v58, 16, v59
	v_and_b32_e32 v59, 0xffff0000, v59
	v_pk_fma_f32 v[56:57], v[84:85], v[60:61], v[56:57]
	ds_bpermute_b32 v63, v193, v105
	v_pk_fma_f32 v[56:57], v[80:81], v[58:59], v[56:57]
	ds_bpermute_b32 v111, v225, v101
	v_pk_add_f32 v[56:57], v[88:89], v[56:57]
	v_lshlrev_b32_e32 v60, 16, v105
	v_mul_f32_e32 v58, 0xbfb8aa3b, v56
	v_mul_f32_e32 v59, 0xbfb8aa3b, v57
	v_exp_f32_e32 v58, v58
	v_exp_f32_e32 v59, v59
	s_waitcnt lgkmcnt(1)
	v_cndmask_b32_e64 v120, v63, v131, s[4:5]
	s_waitcnt lgkmcnt(0)
	v_cndmask_b32_e64 v121, v137, v111, s[6:7]
	v_add_f32_e32 v58, 1.0, v58
	v_add_f32_e32 v59, 1.0, v59
	v_rcp_f32_e32 v58, v58
	v_rcp_f32_e32 v59, v59
	v_and_b32_e32 v61, 0xffff0000, v105
	ds_bpermute_b32 v108, v193, v106
	ds_bpermute_b32 v109, v193, v107
	v_pk_mul_f32 v[56:57], v[56:57], v[58:59]
	v_lshlrev_b32_e32 v58, 16, v121
	v_pk_mul_f32 v[52:53], v[52:53], v[56:57]
	v_lshlrev_b32_e32 v56, 16, v120
	v_and_b32_e32 v57, 0xffff0000, v120
	v_pk_mul_f32 v[56:57], v[94:95], v[56:57]
	v_and_b32_e32 v59, 0xffff0000, v121
	v_pk_fma_f32 v[56:57], v[86:87], v[60:61], v[56:57]
	s_waitcnt lgkmcnt(1)
	v_cndmask_b32_e64 v122, v108, v134, s[4:5]
	v_pk_fma_f32 v[56:57], v[82:83], v[58:59], v[56:57]
	v_lshlrev_b32_e32 v60, 16, v106
	v_pk_add_f32 v[56:57], v[90:91], v[56:57]
	v_and_b32_e32 v61, 0xffff0000, v106
	v_mul_f32_e32 v58, 0xbfb8aa3b, v56
	v_mul_f32_e32 v59, 0xbfb8aa3b, v57
	v_exp_f32_e32 v58, v58
	v_exp_f32_e32 v59, v59
	s_waitcnt lgkmcnt(0)
	v_cndmask_b32_e64 v128, v109, v135, s[4:5]
	v_add_f32_e32 v58, 1.0, v58
	v_add_f32_e32 v59, 1.0, v59
	v_rcp_f32_e32 v58, v58
	v_rcp_f32_e32 v59, v59
	s_nop 0
	v_pk_mul_f32 v[56:57], v[56:57], v[58:59]
	s_nop 0
	v_pk_mul_f32 v[54:55], v[54:55], v[56:57]
	v_lshlrev_b32_e32 v56, 16, v122
	v_and_b32_e32 v57, 0xffff0000, v122
	v_pk_mul_f32 v[56:57], v[76:77], v[56:57]
	v_lshlrev_b32_e32 v58, 16, v123
	v_and_b32_e32 v59, 0xffff0000, v123
	v_pk_fma_f32 v[56:57], v[68:69], v[60:61], v[56:57]
	v_lshlrev_b32_e32 v60, 16, v107
	v_pk_fma_f32 v[56:57], v[64:65], v[58:59], v[56:57]
	v_and_b32_e32 v61, 0xffff0000, v107
	v_pk_add_f32 v[56:57], v[72:73], v[56:57]
	s_nop 0
	v_mul_f32_e32 v58, 0xbfb8aa3b, v56
	v_mul_f32_e32 v59, 0xbfb8aa3b, v57
	v_exp_f32_e32 v58, v58
	v_exp_f32_e32 v59, v59
	v_add_f32_e32 v58, 1.0, v58
	v_add_f32_e32 v59, 1.0, v59
	v_rcp_f32_e32 v58, v58
	v_rcp_f32_e32 v59, v59
	s_nop 0
	v_pk_mul_f32 v[56:57], v[56:57], v[58:59]
	s_nop 0
	v_pk_mul_f32 v[56:57], v[48:49], v[56:57]
	v_lshlrev_b32_e32 v48, 16, v128
	v_and_b32_e32 v49, 0xffff0000, v128
	v_pk_mul_f32 v[48:49], v[78:79], v[48:49]
	v_lshlrev_b32_e32 v58, 16, v129
	v_and_b32_e32 v59, 0xffff0000, v129
	v_pk_fma_f32 v[48:49], v[70:71], v[60:61], v[48:49]
	ds_bpermute_b32 v60, v225, v98
	v_pk_fma_f32 v[48:49], v[66:67], v[58:59], v[48:49]
	ds_bpermute_b32 v61, v225, v99
	v_pk_add_f32 v[48:49], v[74:75], v[48:49]
	s_waitcnt lgkmcnt(1)
	v_cndmask_b32_e64 v105, v118, v60, s[6:7]
	v_mul_f32_e32 v58, 0xbfb8aa3b, v48
	v_mul_f32_e32 v59, 0xbfb8aa3b, v49
	v_exp_f32_e32 v58, v58
	v_exp_f32_e32 v59, v59
	s_waitcnt lgkmcnt(0)
	v_cndmask_b32_e64 v107, v119, v61, s[6:7]
	v_add_f32_e32 v58, 1.0, v58
	v_add_f32_e32 v59, 1.0, v59
	v_rcp_f32_e32 v58, v58
	v_rcp_f32_e32 v59, v59
	s_nop 0
	v_pk_mul_f32 v[48:49], v[48:49], v[58:59]
	s_nop 0
	v_pk_mul_f32 v[58:59], v[50:51], v[48:49]
	v_cvt_pk_bf16_f32 v49, v54, v55
	ds_bpermute_b32 v54, v193, v100
	v_cvt_pk_bf16_f32 v51, v58, v59
	ds_bpermute_b32 v58, v225, v96
	v_cvt_pk_bf16_f32 v48, v52, v53
	v_cvt_pk_bf16_f32 v50, v56, v57
	global_store_dwordx4 v[146:147], v[48:51], off offset:256
	v_lshlrev_b32_e32 v52, 16, v100
	v_and_b32_e32 v53, 0xffff0000, v100
	s_waitcnt lgkmcnt(1)
	v_cndmask_b32_e64 v49, v54, v62, s[4:5]
	v_lshlrev_b32_e32 v48, 16, v49
	v_and_b32_e32 v49, 0xffff0000, v49
	s_waitcnt lgkmcnt(0)
	v_cndmask_b32_e64 v51, v110, v58, s[6:7]
	v_pk_mul_f32 v[48:49], v[92:93], v[48:49]
	v_lshlrev_b32_e32 v50, 16, v51
	v_and_b32_e32 v51, 0xffff0000, v51
	v_pk_fma_f32 v[48:49], v[84:85], v[52:53], v[48:49]
	ds_bpermute_b32 v55, v193, v101
	v_pk_fma_f32 v[48:49], v[80:81], v[50:51], v[48:49]
	ds_bpermute_b32 v59, v225, v97
	v_pk_add_f32 v[48:49], v[88:89], v[48:49]
	v_lshlrev_b32_e32 v52, 16, v101
	v_mul_f32_e32 v50, 0xbfb8aa3b, v48
	v_mul_f32_e32 v51, 0xbfb8aa3b, v49
	v_exp_f32_e32 v50, v50
	v_exp_f32_e32 v51, v51
	s_waitcnt lgkmcnt(1)
	v_cndmask_b32_e64 v62, v55, v63, s[4:5]
	s_waitcnt lgkmcnt(0)
	v_cndmask_b32_e64 v63, v111, v59, s[6:7]
	v_add_f32_e32 v50, 1.0, v50
	v_add_f32_e32 v51, 1.0, v51
	v_rcp_f32_e32 v50, v50
	v_rcp_f32_e32 v51, v51
	v_and_b32_e32 v53, 0xffff0000, v101
	ds_bpermute_b32 v56, v193, v102
	ds_bpermute_b32 v57, v193, v103
	v_pk_mul_f32 v[48:49], v[48:49], v[50:51]
	v_lshlrev_b32_e32 v50, 16, v63
	v_pk_mul_f32 v[44:45], v[44:45], v[48:49]
	v_lshlrev_b32_e32 v48, 16, v62
	v_and_b32_e32 v49, 0xffff0000, v62
	v_pk_mul_f32 v[48:49], v[94:95], v[48:49]
	v_and_b32_e32 v51, 0xffff0000, v63
	v_pk_fma_f32 v[48:49], v[86:87], v[52:53], v[48:49]
	s_waitcnt lgkmcnt(1)
	v_cndmask_b32_e64 v104, v56, v108, s[4:5]
	v_pk_fma_f32 v[48:49], v[82:83], v[50:51], v[48:49]
	v_lshlrev_b32_e32 v52, 16, v102
	v_pk_add_f32 v[48:49], v[90:91], v[48:49]
	v_and_b32_e32 v53, 0xffff0000, v102
	v_mul_f32_e32 v50, 0xbfb8aa3b, v48
	v_mul_f32_e32 v51, 0xbfb8aa3b, v49
	v_exp_f32_e32 v50, v50
	v_exp_f32_e32 v51, v51
	s_waitcnt lgkmcnt(0)
	v_cndmask_b32_e64 v106, v57, v109, s[4:5]
	v_add_f32_e32 v50, 1.0, v50
	v_add_f32_e32 v51, 1.0, v51
	v_rcp_f32_e32 v50, v50
	v_rcp_f32_e32 v51, v51
	s_nop 0
	v_pk_mul_f32 v[48:49], v[48:49], v[50:51]
	s_nop 0
	v_pk_mul_f32 v[46:47], v[46:47], v[48:49]
	v_lshlrev_b32_e32 v48, 16, v104
	v_and_b32_e32 v49, 0xffff0000, v104
	v_pk_mul_f32 v[48:49], v[76:77], v[48:49]
	v_lshlrev_b32_e32 v50, 16, v105
	v_and_b32_e32 v51, 0xffff0000, v105
	v_pk_fma_f32 v[48:49], v[68:69], v[52:53], v[48:49]
	v_lshlrev_b32_e32 v52, 16, v103
	v_pk_fma_f32 v[48:49], v[64:65], v[50:51], v[48:49]
	v_and_b32_e32 v53, 0xffff0000, v103
	v_pk_add_f32 v[48:49], v[72:73], v[48:49]
	s_nop 0
	v_mul_f32_e32 v50, 0xbfb8aa3b, v48
	v_mul_f32_e32 v51, 0xbfb8aa3b, v49
	v_exp_f32_e32 v50, v50
	v_exp_f32_e32 v51, v51
	v_add_f32_e32 v50, 1.0, v50
	v_add_f32_e32 v51, 1.0, v51
	v_rcp_f32_e32 v50, v50
	v_rcp_f32_e32 v51, v51
	s_nop 0
	v_pk_mul_f32 v[48:49], v[48:49], v[50:51]
	s_nop 0
	v_pk_mul_f32 v[48:49], v[40:41], v[48:49]
	v_lshlrev_b32_e32 v40, 16, v106
	v_and_b32_e32 v41, 0xffff0000, v106
	v_pk_mul_f32 v[40:41], v[78:79], v[40:41]
	v_lshlrev_b32_e32 v50, 16, v107
	v_and_b32_e32 v51, 0xffff0000, v107
	v_pk_fma_f32 v[40:41], v[70:71], v[52:53], v[40:41]
	s_nop 0
	v_pk_fma_f32 v[40:41], v[66:67], v[50:51], v[40:41]
	s_nop 0
	v_pk_add_f32 v[40:41], v[74:75], v[40:41]
	s_nop 0
	v_mul_f32_e32 v50, 0xbfb8aa3b, v40
	v_mul_f32_e32 v51, 0xbfb8aa3b, v41
	v_exp_f32_e32 v50, v50
	v_exp_f32_e32 v51, v51
	v_add_f32_e32 v50, 1.0, v50
	v_add_f32_e32 v51, 1.0, v51
	v_rcp_f32_e32 v50, v50
	v_rcp_f32_e32 v51, v51
	s_nop 0
	v_pk_mul_f32 v[40:41], v[40:41], v[50:51]
	s_nop 0
	v_pk_mul_f32 v[50:51], v[42:43], v[40:41]
	v_cvt_pk_bf16_f32 v40, v44, v45
	v_cvt_pk_bf16_f32 v41, v46, v47
	v_cvt_pk_bf16_f32 v42, v48, v49
	v_cvt_pk_bf16_f32 v43, v50, v51
	global_store_dwordx4 v[148:149], v[40:43], off offset:256
	ds_bpermute_b32 v40, v193, v96
	ds_bpermute_b32 v41, v193, v97
	ds_bpermute_b32 v42, v193, v98
	ds_bpermute_b32 v43, v193, v99
	v_cndmask_b32_e64 v45, v58, v117, s[6:7]
	s_waitcnt lgkmcnt(3)
	v_cndmask_b32_e64 v44, v40, v54, s[4:5]
	s_waitcnt lgkmcnt(2)
	v_cndmask_b32_e64 v46, v41, v55, s[4:5]
	v_lshlrev_b32_e32 v40, 16, v44
	v_and_b32_e32 v41, 0xffff0000, v44
	s_waitcnt lgkmcnt(1)
	v_cndmask_b32_e64 v48, v42, v56, s[4:5]
	s_waitcnt lgkmcnt(0)
	v_cndmask_b32_e64 v50, v43, v57, s[4:5]
	v_lshlrev_b32_e32 v42, 16, v45
	v_and_b32_e32 v43, 0xffff0000, v45
	v_pk_mul_f32 v[40:41], v[92:93], v[40:41]
	v_lshlrev_b32_e32 v44, 16, v96
	v_and_b32_e32 v45, 0xffff0000, v96
	v_pk_fma_f32 v[40:41], v[84:85], v[44:45], v[40:41]
	v_cndmask_b32_e64 v47, v59, v116, s[6:7]
	v_pk_fma_f32 v[40:41], v[80:81], v[42:43], v[40:41]
	v_lshlrev_b32_e32 v44, 16, v97
	v_pk_add_f32 v[40:41], v[88:89], v[40:41]
	v_and_b32_e32 v45, 0xffff0000, v97
	v_mul_f32_e32 v42, 0xbfb8aa3b, v40
	v_mul_f32_e32 v43, 0xbfb8aa3b, v41
	v_exp_f32_e32 v42, v42
	v_exp_f32_e32 v43, v43
	v_cndmask_b32_e64 v49, v60, v115, s[6:7]
	v_cndmask_b32_e64 v51, v61, v114, s[6:7]
	v_add_f32_e32 v42, 1.0, v42
	v_add_f32_e32 v43, 1.0, v43
	v_rcp_f32_e32 v42, v42
	v_rcp_f32_e32 v43, v43
	s_nop 0
	v_pk_mul_f32 v[40:41], v[40:41], v[42:43]
	s_nop 0
	v_pk_mul_f32 v[36:37], v[36:37], v[40:41]
	v_lshlrev_b32_e32 v40, 16, v46
	v_and_b32_e32 v41, 0xffff0000, v46
	v_pk_mul_f32 v[40:41], v[94:95], v[40:41]
	v_lshlrev_b32_e32 v42, 16, v47
	v_and_b32_e32 v43, 0xffff0000, v47
	v_pk_fma_f32 v[40:41], v[86:87], v[44:45], v[40:41]
	v_lshlrev_b32_e32 v44, 16, v98
	v_pk_fma_f32 v[40:41], v[82:83], v[42:43], v[40:41]
	v_and_b32_e32 v45, 0xffff0000, v98
	v_pk_add_f32 v[40:41], v[90:91], v[40:41]
	s_nop 0
	v_mul_f32_e32 v42, 0xbfb8aa3b, v40
	v_mul_f32_e32 v43, 0xbfb8aa3b, v41
	v_exp_f32_e32 v42, v42
	v_exp_f32_e32 v43, v43
	v_add_f32_e32 v42, 1.0, v42
	v_add_f32_e32 v43, 1.0, v43
	v_rcp_f32_e32 v42, v42
	v_rcp_f32_e32 v43, v43
	s_nop 0
	v_pk_mul_f32 v[40:41], v[40:41], v[42:43]
	s_nop 0
	v_pk_mul_f32 v[38:39], v[38:39], v[40:41]
	v_lshlrev_b32_e32 v40, 16, v48
	v_and_b32_e32 v41, 0xffff0000, v48
	v_pk_mul_f32 v[40:41], v[76:77], v[40:41]
	v_lshlrev_b32_e32 v42, 16, v49
	v_and_b32_e32 v43, 0xffff0000, v49
	v_pk_fma_f32 v[40:41], v[68:69], v[44:45], v[40:41]
	v_lshlrev_b32_e32 v44, 16, v99
	v_pk_fma_f32 v[40:41], v[64:65], v[42:43], v[40:41]
	v_and_b32_e32 v45, 0xffff0000, v99
	v_pk_add_f32 v[40:41], v[72:73], v[40:41]
	s_nop 0
	v_mul_f32_e32 v42, 0xbfb8aa3b, v40
	v_mul_f32_e32 v43, 0xbfb8aa3b, v41
	v_exp_f32_e32 v42, v42
	v_exp_f32_e32 v43, v43
	v_add_f32_e32 v42, 1.0, v42
	v_add_f32_e32 v43, 1.0, v43
	v_rcp_f32_e32 v42, v42
	v_rcp_f32_e32 v43, v43
	s_nop 0
	v_pk_mul_f32 v[40:41], v[40:41], v[42:43]
	s_nop 0
	v_pk_mul_f32 v[40:41], v[32:33], v[40:41]
	v_lshlrev_b32_e32 v32, 16, v50
	v_and_b32_e32 v33, 0xffff0000, v50
	v_pk_mul_f32 v[32:33], v[78:79], v[32:33]
	v_lshlrev_b32_e32 v42, 16, v51
	v_and_b32_e32 v43, 0xffff0000, v51
	v_pk_fma_f32 v[32:33], v[70:71], v[44:45], v[32:33]
	s_nop 0
	v_pk_fma_f32 v[32:33], v[66:67], v[42:43], v[32:33]
	s_nop 0
	v_pk_add_f32 v[32:33], v[74:75], v[32:33]
	s_nop 0
	v_mul_f32_e32 v42, 0xbfb8aa3b, v32
	v_mul_f32_e32 v43, 0xbfb8aa3b, v33
	v_exp_f32_e32 v42, v42
	v_exp_f32_e32 v43, v43
	v_add_f32_e32 v42, 1.0, v42
	v_add_f32_e32 v43, 1.0, v43
	v_rcp_f32_e32 v42, v42
	v_rcp_f32_e32 v43, v43
	s_nop 0
	v_pk_mul_f32 v[32:33], v[32:33], v[42:43]
	s_nop 0
	v_pk_mul_f32 v[42:43], v[34:35], v[32:33]
	v_cvt_pk_bf16_f32 v32, v36, v37
	v_cvt_pk_bf16_f32 v33, v38, v39
	v_cvt_pk_bf16_f32 v34, v40, v41
	v_cvt_pk_bf16_f32 v35, v42, v43
	global_store_dwordx4 v[144:145], v[32:35], off offset:256
	global_load_dwordx4 v[48:51], v[150:151], off offset:256
	global_load_dwordx4 v[44:47], v[152:153], off offset:256
	global_load_dwordx4 v[40:43], v[154:155], off offset:256
	global_load_dwordx4 v[32:35], v[158:159], off offset:256
	global_load_dwordx4 v[52:55], v[162:163], off offset:256
	global_load_dwordx4 v[36:39], v[160:161], off offset:256
	s_waitcnt vmcnt(5)
	ds_bpermute_b32 v58, v193, v48
	ds_bpermute_b32 v56, v225, v48
	ds_bpermute_b32 v59, v193, v49
	s_waitcnt vmcnt(4)
	ds_bpermute_b32 v96, v225, v44
	ds_bpermute_b32 v57, v225, v49
	ds_bpermute_b32 v60, v193, v50
	ds_bpermute_b32 v62, v193, v51
	ds_bpermute_b32 v97, v225, v45
	s_waitcnt vmcnt(1)
	v_cndmask_b32_e64 v52, v52, 0, s[22:23]
	v_cndmask_b32_e64 v53, v53, 0, s[22:23]
	s_waitcnt lgkmcnt(7)
	v_cndmask_b32_e64 v100, v58, v52, s[4:5]
	v_cndmask_b32_e64 v55, v55, 0, s[22:23]
	v_cndmask_b32_e64 v54, v54, 0, s[22:23]
	s_waitcnt lgkmcnt(4)
	v_cndmask_b32_e64 v56, v56, v96, s[6:7]
	v_cndmask_b32_e64 v101, v59, v53, s[4:5]
	v_lshlrev_b32_e32 v52, 16, v100
	v_and_b32_e32 v53, 0xffff0000, v100
	s_waitcnt lgkmcnt(0)
	v_cndmask_b32_e64 v102, v57, v97, s[6:7]
	v_cndmask_b32_e64 v103, v60, v54, s[4:5]
	v_cndmask_b32_e64 v104, v62, v55, s[4:5]
	v_lshlrev_b32_e32 v54, 16, v56
	v_and_b32_e32 v55, 0xffff0000, v56
	v_pk_mul_f32 v[52:53], v[92:93], v[52:53]
	v_lshlrev_b32_e32 v56, 16, v48
	v_and_b32_e32 v57, 0xffff0000, v48
	v_pk_fma_f32 v[52:53], v[84:85], v[56:57], v[52:53]
	ds_bpermute_b32 v61, v225, v50
	v_pk_fma_f32 v[52:53], v[80:81], v[54:55], v[52:53]
	ds_bpermute_b32 v98, v225, v46
	v_pk_add_f32 v[52:53], v[88:89], v[52:53]
	ds_bpermute_b32 v63, v225, v51
	v_mul_f32_e32 v48, 0xbfb8aa3b, v52
	v_exp_f32_e32 v48, v48
	s_waitcnt lgkmcnt(1)
	v_cndmask_b32_e64 v61, v61, v98, s[6:7]
	ds_bpermute_b32 v99, v225, v47
	v_add_f32_e32 v48, 1.0, v48
	v_rcp_f32_e32 v54, v48
	v_mul_f32_e32 v48, 0xbfb8aa3b, v53
	v_exp_f32_e32 v48, v48
	s_waitcnt lgkmcnt(0)
	v_cndmask_b32_e64 v63, v63, v99, s[6:7]
	v_add_f32_e32 v48, 1.0, v48
	v_rcp_f32_e32 v55, v48
	v_lshlrev_b32_e32 v48, 16, v49
	v_and_b32_e32 v49, 0xffff0000, v49
	v_pk_mul_f32 v[52:53], v[52:53], v[54:55]
	s_nop 0
	v_pk_mul_f32 v[28:29], v[28:29], v[52:53]
	v_lshlrev_b32_e32 v52, 16, v101
	v_and_b32_e32 v53, 0xffff0000, v101
	v_pk_mul_f32 v[52:53], v[94:95], v[52:53]
	v_lshlrev_b32_e32 v54, 16, v102
	v_and_b32_e32 v55, 0xffff0000, v102
	v_pk_fma_f32 v[48:49], v[86:87], v[48:49], v[52:53]
	s_nop 0
	v_pk_fma_f32 v[48:49], v[82:83], v[54:55], v[48:49]
	v_lshlrev_b32_e32 v54, 16, v50
	v_pk_add_f32 v[48:49], v[90:91], v[48:49]
	v_and_b32_e32 v55, 0xffff0000, v50
	v_mul_f32_e32 v52, 0xbfb8aa3b, v48
	v_mul_f32_e32 v53, 0xbfb8aa3b, v49
	v_exp_f32_e32 v52, v52
	v_exp_f32_e32 v53, v53
	v_add_f32_e32 v52, 1.0, v52
	v_add_f32_e32 v53, 1.0, v53
	v_rcp_f32_e32 v52, v52
	v_rcp_f32_e32 v53, v53
	s_nop 0
	v_pk_mul_f32 v[48:49], v[48:49], v[52:53]
	s_nop 0
	v_pk_mul_f32 v[30:31], v[30:31], v[48:49]
	v_lshlrev_b32_e32 v48, 16, v103
	v_and_b32_e32 v49, 0xffff0000, v103
	v_pk_mul_f32 v[48:49], v[76:77], v[48:49]
	v_lshlrev_b32_e32 v52, 16, v61
	v_and_b32_e32 v53, 0xffff0000, v61
	v_pk_fma_f32 v[48:49], v[68:69], v[54:55], v[48:49]
	s_nop 0
	v_pk_fma_f32 v[48:49], v[64:65], v[52:53], v[48:49]
	s_nop 0
	v_pk_add_f32 v[48:49], v[72:73], v[48:49]
	s_nop 0
	v_mul_f32_e32 v50, 0xbfb8aa3b, v48
	v_exp_f32_e32 v50, v50
	s_nop 0
	v_add_f32_e32 v50, 1.0, v50
	v_rcp_f32_e32 v52, v50
	v_mul_f32_e32 v50, 0xbfb8aa3b, v49
	v_exp_f32_e32 v50, v50
	s_nop 0
	v_add_f32_e32 v50, 1.0, v50
	v_rcp_f32_e32 v53, v50
	v_lshlrev_b32_e32 v50, 16, v51
	v_and_b32_e32 v51, 0xffff0000, v51
	v_pk_mul_f32 v[48:49], v[48:49], v[52:53]
	s_nop 0
	v_pk_mul_f32 v[48:49], v[24:25], v[48:49]
	v_lshlrev_b32_e32 v24, 16, v104
	v_and_b32_e32 v25, 0xffff0000, v104
	v_pk_mul_f32 v[24:25], v[78:79], v[24:25]
	v_lshlrev_b32_e32 v52, 16, v63
	v_and_b32_e32 v53, 0xffff0000, v63
	v_pk_fma_f32 v[24:25], v[70:71], v[50:51], v[24:25]
	s_nop 0
	v_pk_fma_f32 v[24:25], v[66:67], v[52:53], v[24:25]
	ds_bpermute_b32 v52, v225, v42
	v_pk_add_f32 v[24:25], v[74:75], v[24:25]
	ds_bpermute_b32 v53, v225, v43
	v_mul_f32_e32 v50, 0xbfb8aa3b, v24
	v_mul_f32_e32 v51, 0xbfb8aa3b, v25
	v_exp_f32_e32 v50, v50
	v_exp_f32_e32 v51, v51
	s_waitcnt lgkmcnt(1)
	v_cndmask_b32_e64 v57, v98, v52, s[6:7]
	v_add_f32_e32 v50, 1.0, v50
	v_add_f32_e32 v51, 1.0, v51
	v_rcp_f32_e32 v50, v50
	v_rcp_f32_e32 v51, v51
	s_nop 0
	v_pk_mul_f32 v[24:25], v[24:25], v[50:51]
	s_nop 0
	v_pk_mul_f32 v[50:51], v[26:27], v[24:25]
	v_cvt_pk_bf16_f32 v25, v30, v31
	ds_bpermute_b32 v30, v193, v44
	v_cvt_pk_bf16_f32 v27, v50, v51
	ds_bpermute_b32 v50, v225, v40
	v_cvt_pk_bf16_f32 v24, v28, v29
	v_cvt_pk_bf16_f32 v26, v48, v49
	global_store_dwordx4 v[124:125], v[24:27], off offset:256
	v_lshlrev_b32_e32 v28, 16, v44
	v_and_b32_e32 v29, 0xffff0000, v44
	s_waitcnt lgkmcnt(1)
	v_cndmask_b32_e64 v25, v30, v58, s[4:5]
	v_lshlrev_b32_e32 v24, 16, v25
	v_and_b32_e32 v25, 0xffff0000, v25
	s_waitcnt lgkmcnt(0)
	v_cndmask_b32_e64 v27, v96, v50, s[6:7]
	v_pk_mul_f32 v[24:25], v[92:93], v[24:25]
	v_lshlrev_b32_e32 v26, 16, v27
	v_and_b32_e32 v27, 0xffff0000, v27
	v_pk_fma_f32 v[24:25], v[84:85], v[28:29], v[24:25]
	ds_bpermute_b32 v31, v193, v45
	v_pk_fma_f32 v[24:25], v[80:81], v[26:27], v[24:25]
	ds_bpermute_b32 v51, v225, v41
	v_pk_add_f32 v[24:25], v[88:89], v[24:25]
	v_lshlrev_b32_e32 v28, 16, v45
	v_mul_f32_e32 v26, 0xbfb8aa3b, v24
	v_mul_f32_e32 v27, 0xbfb8aa3b, v25
	v_exp_f32_e32 v26, v26
	v_exp_f32_e32 v27, v27
	s_waitcnt lgkmcnt(1)
	v_cndmask_b32_e64 v54, v31, v59, s[4:5]
	s_waitcnt lgkmcnt(0)
	v_cndmask_b32_e64 v55, v97, v51, s[6:7]
	v_add_f32_e32 v26, 1.0, v26
	v_add_f32_e32 v27, 1.0, v27
	v_rcp_f32_e32 v26, v26
	v_rcp_f32_e32 v27, v27
	v_and_b32_e32 v29, 0xffff0000, v45
	ds_bpermute_b32 v48, v193, v46
	ds_bpermute_b32 v49, v193, v47
	v_pk_mul_f32 v[24:25], v[24:25], v[26:27]
	v_lshlrev_b32_e32 v26, 16, v55
	v_pk_mul_f32 v[20:21], v[20:21], v[24:25]
	v_lshlrev_b32_e32 v24, 16, v54
	v_and_b32_e32 v25, 0xffff0000, v54
	v_pk_mul_f32 v[24:25], v[94:95], v[24:25]
	v_and_b32_e32 v27, 0xffff0000, v55
	v_pk_fma_f32 v[24:25], v[86:87], v[28:29], v[24:25]
	s_waitcnt lgkmcnt(1)
	v_cndmask_b32_e64 v56, v48, v60, s[4:5]
	v_pk_fma_f32 v[24:25], v[82:83], v[26:27], v[24:25]
	v_lshlrev_b32_e32 v28, 16, v46
	v_pk_add_f32 v[24:25], v[90:91], v[24:25]
	v_and_b32_e32 v29, 0xffff0000, v46
	v_mul_f32_e32 v26, 0xbfb8aa3b, v24
	v_mul_f32_e32 v27, 0xbfb8aa3b, v25
	v_exp_f32_e32 v26, v26
	v_exp_f32_e32 v27, v27
	s_waitcnt lgkmcnt(0)
	v_cndmask_b32_e64 v58, v49, v62, s[4:5]
	v_cndmask_b32_e64 v59, v99, v53, s[6:7]
	v_add_f32_e32 v26, 1.0, v26
	v_add_f32_e32 v27, 1.0, v27
	v_rcp_f32_e32 v26, v26
	v_rcp_f32_e32 v27, v27
	s_nop 0
	v_pk_mul_f32 v[24:25], v[24:25], v[26:27]
	s_nop 0
	v_pk_mul_f32 v[22:23], v[22:23], v[24:25]
	v_lshlrev_b32_e32 v24, 16, v56
	v_and_b32_e32 v25, 0xffff0000, v56
	v_pk_mul_f32 v[24:25], v[76:77], v[24:25]
	v_lshlrev_b32_e32 v26, 16, v57
	v_and_b32_e32 v27, 0xffff0000, v57
	v_pk_fma_f32 v[24:25], v[68:69], v[28:29], v[24:25]
	v_lshlrev_b32_e32 v28, 16, v47
	v_pk_fma_f32 v[24:25], v[64:65], v[26:27], v[24:25]
	v_and_b32_e32 v29, 0xffff0000, v47
	v_pk_add_f32 v[24:25], v[72:73], v[24:25]
	s_nop 0
	v_mul_f32_e32 v26, 0xbfb8aa3b, v24
	v_mul_f32_e32 v27, 0xbfb8aa3b, v25
	v_exp_f32_e32 v26, v26
	v_exp_f32_e32 v27, v27
	v_add_f32_e32 v26, 1.0, v26
	v_add_f32_e32 v27, 1.0, v27
	v_rcp_f32_e32 v26, v26
	v_rcp_f32_e32 v27, v27
	s_nop 0
	v_pk_mul_f32 v[24:25], v[24:25], v[26:27]
	s_nop 0
	v_pk_mul_f32 v[24:25], v[16:17], v[24:25]
	v_lshlrev_b32_e32 v16, 16, v58
	v_and_b32_e32 v17, 0xffff0000, v58
	v_pk_mul_f32 v[16:17], v[78:79], v[16:17]
	v_lshlrev_b32_e32 v26, 16, v59
	v_and_b32_e32 v27, 0xffff0000, v59
	v_pk_fma_f32 v[16:17], v[70:71], v[28:29], v[16:17]
	ds_bpermute_b32 v28, v225, v34
	v_pk_fma_f32 v[16:17], v[66:67], v[26:27], v[16:17]
	ds_bpermute_b32 v29, v225, v35
	v_pk_add_f32 v[16:17], v[74:75], v[16:17]
	s_waitcnt lgkmcnt(1)
	v_cndmask_b32_e64 v45, v52, v28, s[6:7]
	v_mul_f32_e32 v26, 0xbfb8aa3b, v16
	v_mul_f32_e32 v27, 0xbfb8aa3b, v17
	v_exp_f32_e32 v26, v26
	v_exp_f32_e32 v27, v27
	s_waitcnt lgkmcnt(0)
	v_cndmask_b32_e64 v47, v53, v29, s[6:7]
	v_add_f32_e32 v26, 1.0, v26
	v_add_f32_e32 v27, 1.0, v27
	v_rcp_f32_e32 v26, v26
	v_rcp_f32_e32 v27, v27
	s_nop 0
	v_pk_mul_f32 v[16:17], v[16:17], v[26:27]
	s_nop 0
	v_pk_mul_f32 v[26:27], v[18:19], v[16:17]
	v_cvt_pk_bf16_f32 v17, v22, v23
	ds_bpermute_b32 v22, v193, v40
	v_cvt_pk_bf16_f32 v19, v26, v27
	ds_bpermute_b32 v26, v225, v32
	v_cvt_pk_bf16_f32 v16, v20, v21
	v_cvt_pk_bf16_f32 v18, v24, v25
	global_store_dwordx4 v[126:127], v[16:19], off offset:256
	v_lshlrev_b32_e32 v20, 16, v40
	v_and_b32_e32 v21, 0xffff0000, v40
	s_waitcnt lgkmcnt(1)
	v_cndmask_b32_e64 v17, v22, v30, s[4:5]
	v_lshlrev_b32_e32 v16, 16, v17
	v_and_b32_e32 v17, 0xffff0000, v17
	s_waitcnt lgkmcnt(0)
	v_cndmask_b32_e64 v19, v50, v26, s[6:7]
	v_pk_mul_f32 v[16:17], v[92:93], v[16:17]
	v_lshlrev_b32_e32 v18, 16, v19
	v_and_b32_e32 v19, 0xffff0000, v19
	v_pk_fma_f32 v[16:17], v[84:85], v[20:21], v[16:17]
	ds_bpermute_b32 v23, v193, v41
	v_pk_fma_f32 v[16:17], v[80:81], v[18:19], v[16:17]
	ds_bpermute_b32 v27, v225, v33
	v_pk_add_f32 v[16:17], v[88:89], v[16:17]
	v_lshlrev_b32_e32 v20, 16, v41
	v_mul_f32_e32 v18, 0xbfb8aa3b, v16
	v_mul_f32_e32 v19, 0xbfb8aa3b, v17
	v_exp_f32_e32 v18, v18
	v_exp_f32_e32 v19, v19
	s_waitcnt lgkmcnt(1)
	v_cndmask_b32_e64 v30, v23, v31, s[4:5]
	s_waitcnt lgkmcnt(0)
	v_cndmask_b32_e64 v31, v51, v27, s[6:7]
	v_add_f32_e32 v18, 1.0, v18
	v_add_f32_e32 v19, 1.0, v19
	v_rcp_f32_e32 v18, v18
	v_rcp_f32_e32 v19, v19
	v_and_b32_e32 v21, 0xffff0000, v41
	ds_bpermute_b32 v24, v193, v42
	ds_bpermute_b32 v25, v193, v43
	v_pk_mul_f32 v[16:17], v[16:17], v[18:19]
	v_lshlrev_b32_e32 v18, 16, v31
	v_pk_mul_f32 v[12:13], v[12:13], v[16:17]
	v_lshlrev_b32_e32 v16, 16, v30
	v_and_b32_e32 v17, 0xffff0000, v30
	v_pk_mul_f32 v[16:17], v[94:95], v[16:17]
	v_and_b32_e32 v19, 0xffff0000, v31
	v_pk_fma_f32 v[16:17], v[86:87], v[20:21], v[16:17]
	s_waitcnt lgkmcnt(1)
	v_cndmask_b32_e64 v44, v24, v48, s[4:5]
	v_pk_fma_f32 v[16:17], v[82:83], v[18:19], v[16:17]
	v_lshlrev_b32_e32 v20, 16, v42
	v_pk_add_f32 v[16:17], v[90:91], v[16:17]
	v_and_b32_e32 v21, 0xffff0000, v42
	v_mul_f32_e32 v18, 0xbfb8aa3b, v16
	v_mul_f32_e32 v19, 0xbfb8aa3b, v17
	v_exp_f32_e32 v18, v18
	v_exp_f32_e32 v19, v19
	s_waitcnt lgkmcnt(0)
	v_cndmask_b32_e64 v46, v25, v49, s[4:5]
	v_add_f32_e32 v18, 1.0, v18
	v_add_f32_e32 v19, 1.0, v19
	v_rcp_f32_e32 v18, v18
	v_rcp_f32_e32 v19, v19
	s_nop 0
	v_pk_mul_f32 v[16:17], v[16:17], v[18:19]
	s_nop 0
	v_pk_mul_f32 v[14:15], v[14:15], v[16:17]
	v_lshlrev_b32_e32 v16, 16, v44
	v_and_b32_e32 v17, 0xffff0000, v44
	v_pk_mul_f32 v[16:17], v[76:77], v[16:17]
	v_lshlrev_b32_e32 v18, 16, v45
	v_and_b32_e32 v19, 0xffff0000, v45
	v_pk_fma_f32 v[16:17], v[68:69], v[20:21], v[16:17]
	v_lshlrev_b32_e32 v20, 16, v43
	v_pk_fma_f32 v[16:17], v[64:65], v[18:19], v[16:17]
	v_and_b32_e32 v21, 0xffff0000, v43
	v_pk_add_f32 v[16:17], v[72:73], v[16:17]
	s_nop 0
	v_mul_f32_e32 v18, 0xbfb8aa3b, v16
	v_mul_f32_e32 v19, 0xbfb8aa3b, v17
	v_exp_f32_e32 v18, v18
	v_exp_f32_e32 v19, v19
	v_add_f32_e32 v18, 1.0, v18
	v_add_f32_e32 v19, 1.0, v19
	v_rcp_f32_e32 v18, v18
	v_rcp_f32_e32 v19, v19
	s_nop 0
	v_pk_mul_f32 v[16:17], v[16:17], v[18:19]
	s_nop 0
	v_pk_mul_f32 v[16:17], v[8:9], v[16:17]
	v_lshlrev_b32_e32 v8, 16, v46
	v_and_b32_e32 v9, 0xffff0000, v46
	v_pk_mul_f32 v[8:9], v[78:79], v[8:9]
	v_lshlrev_b32_e32 v18, 16, v47
	v_and_b32_e32 v19, 0xffff0000, v47
	v_pk_fma_f32 v[8:9], v[70:71], v[20:21], v[8:9]
	s_nop 0
	v_pk_fma_f32 v[8:9], v[66:67], v[18:19], v[8:9]
	s_nop 0
	v_pk_add_f32 v[8:9], v[74:75], v[8:9]
	s_nop 0
	v_mul_f32_e32 v18, 0xbfb8aa3b, v8
	v_mul_f32_e32 v19, 0xbfb8aa3b, v9
	v_exp_f32_e32 v18, v18
	v_exp_f32_e32 v19, v19
	v_add_f32_e32 v18, 1.0, v18
	v_add_f32_e32 v19, 1.0, v19
	v_rcp_f32_e32 v18, v18
	v_rcp_f32_e32 v19, v19
	s_nop 0
	v_pk_mul_f32 v[8:9], v[8:9], v[18:19]
	s_nop 0
	v_pk_mul_f32 v[18:19], v[10:11], v[8:9]
	v_cvt_pk_bf16_f32 v8, v12, v13
	v_cvt_pk_bf16_f32 v9, v14, v15
	v_cvt_pk_bf16_f32 v10, v16, v17
	v_cvt_pk_bf16_f32 v11, v18, v19
	global_store_dwordx4 v[132:133], v[8:11], off offset:256
	ds_bpermute_b32 v8, v193, v32
	ds_bpermute_b32 v9, v193, v33
	ds_bpermute_b32 v10, v193, v34
	ds_bpermute_b32 v11, v193, v35
	s_waitcnt vmcnt(3)
	v_cndmask_b32_e64 v12, v39, 0, vcc
	s_waitcnt lgkmcnt(3)
	v_cndmask_b32_e64 v16, v8, v22, s[4:5]
	v_cndmask_b32_e64 v13, v38, 0, vcc
	v_cndmask_b32_e64 v15, v36, 0, vcc
	s_waitcnt lgkmcnt(2)
	v_cndmask_b32_e64 v17, v9, v23, s[4:5]
	v_lshlrev_b32_e32 v8, 16, v16
	v_and_b32_e32 v9, 0xffff0000, v16
	v_cndmask_b32_e64 v15, v26, v15, s[6:7]
	v_cndmask_b32_e64 v19, v28, v13, s[6:7]
	v_cndmask_b32_e64 v21, v29, v12, s[6:7]
	v_pk_mul_f32 v[8:9], v[92:93], v[8:9]
	v_lshlrev_b32_e32 v12, 16, v32
	v_and_b32_e32 v13, 0xffff0000, v32
	s_waitcnt lgkmcnt(1)
	v_cndmask_b32_e64 v18, v10, v24, s[4:5]
	s_waitcnt lgkmcnt(0)
	v_cndmask_b32_e64 v20, v11, v25, s[4:5]
	v_lshlrev_b32_e32 v10, 16, v15
	v_and_b32_e32 v11, 0xffff0000, v15
	v_pk_fma_f32 v[8:9], v[84:85], v[12:13], v[8:9]
	v_cndmask_b32_e64 v14, v37, 0, vcc
	v_pk_fma_f32 v[8:9], v[80:81], v[10:11], v[8:9]
	v_cndmask_b32_e64 v14, v27, v14, s[6:7]
	v_pk_add_f32 v[8:9], v[88:89], v[8:9]
	v_lshlrev_b32_e32 v12, 16, v33
	v_mul_f32_e32 v10, 0xbfb8aa3b, v8
	v_mul_f32_e32 v11, 0xbfb8aa3b, v9
	v_exp_f32_e32 v10, v10
	v_exp_f32_e32 v11, v11
	v_and_b32_e32 v13, 0xffff0000, v33
	s_andn2_b64 vcc, exec, s[68:69]
	v_add_f32_e32 v10, 1.0, v10
	v_add_f32_e32 v11, 1.0, v11
	v_rcp_f32_e32 v10, v10
	v_rcp_f32_e32 v11, v11
	s_nop 0
	v_pk_mul_f32 v[8:9], v[8:9], v[10:11]
	s_nop 0
	v_pk_mul_f32 v[4:5], v[4:5], v[8:9]
	v_lshlrev_b32_e32 v8, 16, v17
	v_and_b32_e32 v9, 0xffff0000, v17
	v_pk_mul_f32 v[8:9], v[94:95], v[8:9]
	v_lshlrev_b32_e32 v10, 16, v14
	v_and_b32_e32 v11, 0xffff0000, v14
	v_pk_fma_f32 v[8:9], v[86:87], v[12:13], v[8:9]
	v_lshlrev_b32_e32 v12, 16, v34
	v_pk_fma_f32 v[8:9], v[82:83], v[10:11], v[8:9]
	v_and_b32_e32 v13, 0xffff0000, v34
	v_pk_add_f32 v[8:9], v[90:91], v[8:9]
	s_nop 0
	v_mul_f32_e32 v10, 0xbfb8aa3b, v8
	v_mul_f32_e32 v11, 0xbfb8aa3b, v9
	v_exp_f32_e32 v10, v10
	v_exp_f32_e32 v11, v11
	v_add_f32_e32 v10, 1.0, v10
	v_add_f32_e32 v11, 1.0, v11
	v_rcp_f32_e32 v10, v10
	v_rcp_f32_e32 v11, v11
	s_nop 0
	v_pk_mul_f32 v[8:9], v[8:9], v[10:11]
	s_nop 0
	v_pk_mul_f32 v[6:7], v[6:7], v[8:9]
	v_lshlrev_b32_e32 v8, 16, v18
	v_and_b32_e32 v9, 0xffff0000, v18
	v_pk_mul_f32 v[8:9], v[76:77], v[8:9]
	v_lshlrev_b32_e32 v10, 16, v19
	v_and_b32_e32 v11, 0xffff0000, v19
	v_pk_fma_f32 v[8:9], v[68:69], v[12:13], v[8:9]
	v_lshlrev_b32_e32 v12, 16, v35
	v_pk_fma_f32 v[8:9], v[64:65], v[10:11], v[8:9]
	v_and_b32_e32 v13, 0xffff0000, v35
	v_pk_add_f32 v[8:9], v[72:73], v[8:9]
	s_nop 0
	v_mul_f32_e32 v10, 0xbfb8aa3b, v8
	v_mul_f32_e32 v11, 0xbfb8aa3b, v9
	v_exp_f32_e32 v10, v10
	v_exp_f32_e32 v11, v11
	v_add_f32_e32 v10, 1.0, v10
	v_add_f32_e32 v11, 1.0, v11
	v_rcp_f32_e32 v10, v10
	v_rcp_f32_e32 v11, v11
	s_nop 0
	v_pk_mul_f32 v[8:9], v[8:9], v[10:11]
	s_nop 0
	v_pk_mul_f32 v[8:9], v[0:1], v[8:9]
	v_lshlrev_b32_e32 v0, 16, v20
	v_and_b32_e32 v1, 0xffff0000, v20
	v_pk_mul_f32 v[0:1], v[78:79], v[0:1]
	v_lshlrev_b32_e32 v10, 16, v21
	v_and_b32_e32 v11, 0xffff0000, v21
	v_pk_fma_f32 v[0:1], v[70:71], v[12:13], v[0:1]
	s_nop 0
	v_pk_fma_f32 v[0:1], v[66:67], v[10:11], v[0:1]
	s_nop 0
	v_pk_add_f32 v[0:1], v[74:75], v[0:1]
	s_nop 0
	v_mul_f32_e32 v10, 0xbfb8aa3b, v0
	v_mul_f32_e32 v11, 0xbfb8aa3b, v1
	v_exp_f32_e32 v10, v10
	v_exp_f32_e32 v11, v11
	v_add_f32_e32 v10, 1.0, v10
	v_add_f32_e32 v11, 1.0, v11
	v_rcp_f32_e32 v10, v10
	v_rcp_f32_e32 v11, v11
	s_nop 0
	v_pk_mul_f32 v[0:1], v[0:1], v[10:11]
	s_nop 0
	v_pk_mul_f32 v[10:11], v[2:3], v[0:1]
	v_cvt_pk_bf16_f32 v0, v4, v5
	v_cvt_pk_bf16_f32 v1, v6, v7
	v_cvt_pk_bf16_f32 v2, v8, v9
	v_cvt_pk_bf16_f32 v3, v10, v11
	global_store_dwordx4 v[112:113], v[0:3], off offset:256
	s_cbranch_vccnz .LBB0_1053
	s_andn2_b64 vcc, exec, s[36:37]
	s_cbranch_vccnz .LBB0_1052
	s_barrier
	s_branch .LBB0_1052
